# mixer Y stores write-through (sc1) and mixer-barrier leader write-back elided (nowb=npom) on top of v138
# baseline (speedup 1.0000x reference)
; #define LAS __attribute__((address_space(3)))
; __device__ __forceinline__ int crow(int r, int hi) { return (r & 3) + 8 * (r >> 2) + 4 * hi; }
; __device__ __forceinline__ s16x4 vtr(const LAS unsigned char* p) { return __builtin_bit_cast(s16x4, __builtin_amdgcn_ds_read_tr16_b64_v4i16((LAS v4i16_t*)p)); }
; template <bool SAMPLE> ...
;     ...
;         for (int s = 0; s < 2; ++s) { pw[t][s].x = pk_bf16(p[t][8 * s + 0], p[t][8 * s + 1]); pw[t][s].y = pk_bf16(p[t][8 * s + 2], p[t][8 * s + 3]); pw[t][s].z = pk_bf16(p[t][8 * s + 4], p[t][8 * s + 5]); pw[t][s].w = pk_bf16(p[t][8 * s + 6], p[t][8 * s + 7]); }
;     }
;     lsum += __shfl_xor(lsum, 32);
;     const float denom = lsum + __builtin_amdgcn_exp2f(sk - mx);
;     if (hi == 0) wsf[r32] = 1.0f / denom;
;     __builtin_amdgcn_sched_barrier(0);
;     f32x16 o[2];
; #pragma unroll
;     for (int d0 = 0; d0 < 2; ++d0)
; #pragma unroll
;         for (int i = 0; i < 16; ++i) o[d0][i] = 0.f;
;     const int i16 = lane & 15;
;     const LAS unsigned char* vb = Vl + (4 * hi + (i16 >> 2)) * 64 + ((lane >> 4) & 1) * 32 + (i16 & 3) * 8;
; #pragma unroll
;     for (int t = 0; t < 5; ++t)
; #pragma unroll
;         for (int s = 0; s < 2; ++s) {
;             const bf16x8 pa = __builtin_bit_cast(bf16x8, pw[t][s]);
; #pragma unroll
;             for (int d0 = 0; d0 < 2; ++d0) {
;                 const s16x4 vlo = vtr(vb + d0 * vhalf + (32 * t + 16 * s) * 64), vhi = vtr(vb + d0 * vhalf + (32 * t + 16 * s + 8) * 64);
;                 const bf16x8 vf = (bf16x8){vlo[0], vlo[1], vlo[2], vlo[3], vhi[0], vhi[1], vhi[2], vhi[3]};
;                 o[d0] = __builtin_amdgcn_mfma_f32_32x32x16_bf16(pa, vf, o[d0], 0, 0, 0);
;             }
;         }
;     __builtin_amdgcn_sched_barrier(0);
;     asm volatile("s_waitcnt lgkmcnt(0)" ::: "memory");
; #pragma unroll
;     for (int i = 0; i < 16; ++i) {
;         const int qq = crow(i, hi);
;         const float rl = wsf[qq];
; #pragma unroll
;         for (int d0 = 0; d0 < 2; ++d0) ost[qq * 64 + d0 * 32 + r32] = (bf16_t)(pk_bf16(o[d0][i] * rl, 0.f) & 0xffffu);
;     }
.LBB0_458:
	s_or_b64 exec, exec, s[4:5]
	v_ashrrev_i32_e32 v127, 31, v126
	v_cvt_pk_bf16_f32 v32, v32, v33
	v_cvt_pk_bf16_f32 v33, v34, v35
	v_cvt_pk_bf16_f32 v34, v51, v50
	v_cvt_pk_bf16_f32 v35, v49, v48
	v_cvt_pk_bf16_f32 v36, v36, v37
	v_cvt_pk_bf16_f32 v37, v38, v39
	v_cvt_pk_bf16_f32 v38, v83, v82
	v_cvt_pk_bf16_f32 v39, v81, v80
	v_cvt_pk_bf16_f32 v40, v40, v41
	v_cvt_pk_bf16_f32 v41, v42, v43
	v_cvt_pk_bf16_f32 v42, v44, v45
	v_cvt_pk_bf16_f32 v43, v46, v47
	v_cvt_pk_bf16_f32 v44, v96, v97
	v_cvt_pk_bf16_f32 v45, v98, v99
	v_cvt_pk_bf16_f32 v46, v100, v101
	v_cvt_pk_bf16_f32 v47, v102, v103
	v_cvt_pk_bf16_f32 v48, v24, v25
	v_cvt_pk_bf16_f32 v49, v26, v27
	v_cvt_pk_bf16_f32 v50, v28, v29
	v_cvt_pk_bf16_f32 v51, v30, v31
	v_cvt_pk_bf16_f32 v52, v16, v17
	s_waitcnt lgkmcnt(0)
	v_cvt_pk_bf16_f32 v53, v18, v19
	v_cvt_pk_bf16_f32 v54, v20, v21
	v_cvt_pk_bf16_f32 v55, v22, v23
	v_cvt_pk_bf16_f32 v80, v8, v9
	v_cvt_pk_bf16_f32 v81, v10, v11
	v_cvt_pk_bf16_f32 v82, v12, v13
	v_cvt_pk_bf16_f32 v83, v14, v15
	v_cvt_pk_bf16_f32 v84, v0, v1
	v_cvt_pk_bf16_f32 v85, v2, v3
	v_cvt_pk_bf16_f32 v86, v4, v5
	v_cvt_pk_bf16_f32 v87, v6, v7
	v_cvt_pk_bf16_f32 v88, v88, v89
	v_cvt_pk_bf16_f32 v89, v90, v91
	v_cvt_pk_bf16_f32 v90, v92, v93
	v_cvt_pk_bf16_f32 v91, v94, v95
	v_cvt_pk_bf16_f32 v16, v56, v57
	v_cvt_pk_bf16_f32 v17, v58, v59
	v_cvt_pk_bf16_f32 v18, v60, v61
	v_cvt_pk_bf16_f32 v19, v62, v63
	v_add_u32_e32 v0, s70, v115
	v_add3_u32 v60, v0, v117, v118
	ds_read_b64_tr_b16 v[0:1], v60 offset:36864
	ds_read_b64_tr_b16 v[2:3], v60 offset:37376
	ds_read_b64_tr_b16 v[20:21], v60 offset:53248
	ds_read_b64_tr_b16 v[22:23], v60 offset:53760
	ds_read_b64_tr_b16 v[56:57], v60 offset:37888
	ds_read_b64_tr_b16 v[58:59], v60 offset:38400
	s_waitcnt lgkmcnt(4)
	v_mfma_f32_32x32x16_bf16 v[0:15], v[16:19], v[0:3], 0
	s_waitcnt lgkmcnt(2)
	v_mfma_f32_32x32x16_bf16 v[16:31], v[16:19], v[20:23], 0
	s_waitcnt lgkmcnt(0)
	v_mfma_f32_32x32x16_bf16 v[0:15], v[88:91], v[56:59], v[0:15]
	ds_read_b64_tr_b16 v[56:57], v60 offset:54272
	ds_read_b64_tr_b16 v[58:59], v60 offset:54784
	s_waitcnt lgkmcnt(0)
	v_mfma_f32_32x32x16_bf16 v[16:31], v[88:91], v[56:59], v[16:31]
	ds_read_b64_tr_b16 v[56:57], v60 offset:38912
	ds_read_b64_tr_b16 v[58:59], v60 offset:39424
	s_waitcnt lgkmcnt(0)
	v_mfma_f32_32x32x16_bf16 v[0:15], v[84:87], v[56:59], v[0:15]
	ds_read_b64_tr_b16 v[56:57], v60 offset:55296
	ds_read_b64_tr_b16 v[58:59], v60 offset:55808
	s_waitcnt lgkmcnt(0)
	v_mfma_f32_32x32x16_bf16 v[16:31], v[84:87], v[56:59], v[16:31]
	ds_read_b64_tr_b16 v[56:57], v60 offset:39936
	ds_read_b64_tr_b16 v[58:59], v60 offset:40448
	s_waitcnt lgkmcnt(0)
	v_mfma_f32_32x32x16_bf16 v[0:15], v[80:83], v[56:59], v[0:15]
	ds_read_b64_tr_b16 v[56:57], v60 offset:56320
	ds_read_b64_tr_b16 v[58:59], v60 offset:56832
	s_waitcnt lgkmcnt(0)
	v_mfma_f32_32x32x16_bf16 v[16:31], v[80:83], v[56:59], v[16:31]
	ds_read_b64_tr_b16 v[56:57], v60 offset:40960
	ds_read_b64_tr_b16 v[58:59], v60 offset:41472
	s_waitcnt lgkmcnt(0)
	v_mfma_f32_32x32x16_bf16 v[0:15], v[52:55], v[56:59], v[0:15]
	ds_read_b64_tr_b16 v[56:57], v60 offset:57344
	ds_read_b64_tr_b16 v[58:59], v60 offset:57856
	s_waitcnt lgkmcnt(0)
	v_mfma_f32_32x32x16_bf16 v[16:31], v[52:55], v[56:59], v[16:31]
	ds_read_b64_tr_b16 v[52:53], v60 offset:41984
	ds_read_b64_tr_b16 v[54:55], v60 offset:42496
	s_waitcnt lgkmcnt(0)
	v_mfma_f32_32x32x16_bf16 v[0:15], v[48:51], v[52:55], v[0:15]
	ds_read_b64_tr_b16 v[52:53], v60 offset:58368
	ds_read_b64_tr_b16 v[54:55], v60 offset:58880
	s_waitcnt lgkmcnt(0)
	v_mfma_f32_32x32x16_bf16 v[16:31], v[48:51], v[52:55], v[16:31]
	ds_read_b64_tr_b16 v[48:49], v60 offset:43008
	ds_read_b64_tr_b16 v[50:51], v60 offset:43520
	s_waitcnt lgkmcnt(0)
	v_mfma_f32_32x32x16_bf16 v[0:15], v[44:47], v[48:51], v[0:15]
	ds_read_b64_tr_b16 v[48:49], v60 offset:59392
	ds_read_b64_tr_b16 v[50:51], v60 offset:59904
	s_waitcnt lgkmcnt(0)
	v_mfma_f32_32x32x16_bf16 v[16:31], v[44:47], v[48:51], v[16:31]
	ds_read_b64_tr_b16 v[44:45], v60 offset:44032
	ds_read_b64_tr_b16 v[46:47], v60 offset:44544
	s_waitcnt lgkmcnt(0)
	v_mfma_f32_32x32x16_bf16 v[0:15], v[40:43], v[44:47], v[0:15]
	ds_read_b64_tr_b16 v[44:45], v60 offset:60416
	ds_read_b64_tr_b16 v[46:47], v60 offset:60928
	s_waitcnt lgkmcnt(0)
	v_mfma_f32_32x32x16_bf16 v[16:31], v[40:43], v[44:47], v[16:31]
	ds_read_b64_tr_b16 v[40:41], v60 offset:45056
	ds_read_b64_tr_b16 v[42:43], v60 offset:45568
	s_waitcnt lgkmcnt(0)
	v_mfma_f32_32x32x16_bf16 v[0:15], v[36:39], v[40:43], v[0:15]
	ds_read_b64_tr_b16 v[40:41], v60 offset:61440
	ds_read_b64_tr_b16 v[42:43], v60 offset:61952
	s_waitcnt lgkmcnt(0)
	v_mfma_f32_32x32x16_bf16 v[16:31], v[36:39], v[40:43], v[16:31]
	ds_read_b64_tr_b16 v[36:37], v60 offset:46080
	ds_read_b64_tr_b16 v[38:39], v60 offset:46592
	s_waitcnt lgkmcnt(0)
	v_mfma_f32_32x32x16_bf16 v[0:15], v[32:35], v[36:39], v[0:15]
	ds_read_b64_tr_b16 v[36:37], v60 offset:62464
	ds_read_b64_tr_b16 v[38:39], v60 offset:62976
	s_waitcnt lgkmcnt(0)
	v_mfma_f32_32x32x16_bf16 v[16:31], v[32:35], v[36:39], v[16:31]
	s_waitcnt lgkmcnt(0)
	ds_read_b128 v[32:35], v112
	ds_read_b128 v[36:39], v112 offset:32
	v_mov_b32_e32 v125, v173
	s_add_i32 s71, s71, s42
	s_cmpk_gt_i32 s71, 0xff
	s_waitcnt lgkmcnt(1)
	s_nop 1
	v_mul_f32_e32 v0, v0, v32
	s_nop 2
	v_mul_f32_e32 v16, v16, v32
	v_cvt_pk_bf16_f32 v0, v0, s0
	v_cvt_pk_bf16_f32 v16, v16, s0
	ds_write_b16 v116, v0
	ds_write_b16 v116, v16 offset:64
	v_mul_f32_e32 v0, v1, v33
	v_cvt_pk_bf16_f32 v0, v0, s0
	ds_write_b16 v119, v0
	v_mul_f32_e32 v0, v17, v33
	v_cvt_pk_bf16_f32 v0, v0, s0
	ds_write_b16 v119, v0 offset:64
	v_mul_f32_e32 v0, v2, v34
	v_cvt_pk_bf16_f32 v0, v0, s0
	ds_write_b16 v120, v0
	v_mul_f32_e32 v0, v18, v34
	v_cvt_pk_bf16_f32 v0, v0, s0
	ds_write_b16 v120, v0 offset:64
	v_mul_f32_e32 v0, v3, v35
	v_cvt_pk_bf16_f32 v0, v0, s0
	ds_write_b16 v121, v0
	v_mul_f32_e32 v0, v19, v35
	v_cvt_pk_bf16_f32 v0, v0, s0
	ds_write_b16 v121, v0 offset:64
	s_waitcnt lgkmcnt(8)
; #define LAS __attribute__((address_space(3)))
; __device__ __forceinline__ u32x4 pack8(const float (&f)[8]) { u32x4 w; w.x = pk_bf16(f[0], f[1]); w.y = pk_bf16(f[2], f[3]); w.z = pk_bf16(f[4], f[5]); w.w = pk_bf16(f[6], f[7]); return w; }
; __device__ __forceinline__ int crow(int r, int hi) { return (r & 3) + 8 * (r >> 2) + 4 * hi; }
; template <bool SAMPLE> ...
;     ...
; #pragma unroll
;     for (int i = 0; i < 16; ++i) {
;         const int qq = crow(i, hi);
;         const float rl = wsf[qq];
; #pragma unroll
;         for (int d0 = 0; d0 < 2; ++d0) ost[qq * 64 + d0 * 32 + r32] = (bf16_t)(pk_bf16(o[d0][i] * rl, 0.f) & 0xffffu);
;     }
;     asm volatile("s_waitcnt lgkmcnt(0)" ::: "memory");
; #pragma unroll
;     for (int it4 = 0; it4 < 4; ++it4) {
;         const int qq = it4 * 8 + (lane >> 3), ch = lane & 7;
;         const int orow = SAMPLE ? row0 + (qq & 7) : row0 + qq;
;         const int ohead = SAMPLE ? head0 + (qq >> 3) : head0;
;         const u32x4 ow = *(const LAS u32x4*)(ost + qq * 64 + ch * 8);
;         float of[8], zf[8], yv[8];
;         unpack8(ow, of); unpack8(zw[it4], zf);
; #pragma unroll
;         for (int k = 0; k < 8; ++k) yv[k] = of[k] * zf[k];
;         *(u32x4*)(Y + (size_t)orow * D + 512 + ohead * 64 + ch * 8) = pack8(yv);
;     }
	v_mul_f32_e32 v0, v4, v36
	v_cvt_pk_bf16_f32 v0, v0, s0
	ds_write_b16 v122, v0
	v_mul_f32_e32 v0, v20, v36
	v_cvt_pk_bf16_f32 v0, v0, s0
	ds_write_b16 v122, v0 offset:64
	v_mul_f32_e32 v0, v5, v37
	v_cvt_pk_bf16_f32 v0, v0, s0
	ds_write_b16 v123, v0
	v_mul_f32_e32 v0, v21, v37
	v_cvt_pk_bf16_f32 v0, v0, s0
	ds_write_b16 v123, v0 offset:64
	v_mul_f32_e32 v0, v6, v38
	v_cvt_pk_bf16_f32 v0, v0, s0
	ds_write_b16 v135, v0
	v_mul_f32_e32 v0, v22, v38
	v_cvt_pk_bf16_f32 v0, v0, s0
	ds_write_b16 v135, v0 offset:64
	v_mul_f32_e32 v0, v7, v39
	v_cvt_pk_bf16_f32 v0, v0, s0
	ds_write_b16 v134, v0
	ds_read_b128 v[0:3], v112 offset:64
	v_mul_f32_e32 v4, v23, v39
	v_cvt_pk_bf16_f32 v4, v4, s0
	ds_write_b16 v134, v4 offset:64
	ds_read_b128 v[4:7], v112 offset:96
	s_waitcnt lgkmcnt(2)
	v_mul_f32_e32 v8, v8, v0
	v_mul_f32_e32 v0, v24, v0
	v_cvt_pk_bf16_f32 v0, v0, s0
	ds_write_b16 v136, v0 offset:64
	v_mul_f32_e32 v0, v9, v1
	v_cvt_pk_bf16_f32 v0, v0, s0
	ds_write_b16 v137, v0
	v_mul_f32_e32 v0, v25, v1
	v_cvt_pk_bf16_f32 v0, v0, s0
	ds_write_b16 v137, v0 offset:64
	v_mul_f32_e32 v0, v10, v2
	v_cvt_pk_bf16_f32 v0, v0, s0
	ds_write_b16 v138, v0
	v_mul_f32_e32 v0, v26, v2
	v_cvt_pk_bf16_f32 v0, v0, s0
	ds_write_b16 v138, v0 offset:64
	v_mul_f32_e32 v0, v11, v3
	v_cvt_pk_bf16_f32 v0, v0, s0
	ds_write_b16 v139, v0
	v_mul_f32_e32 v0, v27, v3
	v_cvt_pk_bf16_f32 v0, v0, s0
	ds_write_b16 v139, v0 offset:64
	s_waitcnt lgkmcnt(7)
	v_mul_f32_e32 v0, v12, v4
	v_cvt_pk_bf16_f32 v0, v0, s0
	ds_write_b16 v140, v0
	v_mul_f32_e32 v0, v28, v4
	v_cvt_pk_bf16_f32 v0, v0, s0
	ds_write_b16 v140, v0 offset:64
	v_mul_f32_e32 v0, v13, v5
	v_cvt_pk_bf16_f32 v0, v0, s0
	ds_write_b16 v141, v0
	v_mul_f32_e32 v0, v29, v5
	v_cvt_pk_bf16_f32 v0, v0, s0
	ds_write_b16 v141, v0 offset:64
	v_mul_f32_e32 v0, v14, v6
	v_cvt_pk_bf16_f32 v0, v0, s0
	ds_write_b16 v142, v0
	v_mul_f32_e32 v0, v30, v6
	v_cvt_pk_bf16_f32 v0, v0, s0
	ds_write_b16 v142, v0 offset:64
	v_mul_f32_e32 v0, v15, v7
	v_cvt_pk_bf16_f32 v0, v0, s0
	ds_write_b16 v143, v0
	v_mul_f32_e32 v0, v31, v7
	v_cvt_pk_bf16_f32 v8, v8, s0
	v_cvt_pk_bf16_f32 v0, v0, s0
	ds_write_b16 v136, v8
	ds_write_b16 v143, v0 offset:64
	s_waitcnt lgkmcnt(0)
	ds_read_b128 v[0:3], v144
	ds_read_b128 v[4:7], v145
	v_lshlrev_b32_e32 v10, 16, v76
	v_and_b32_e32 v11, 0xffff0000, v76
	v_lshlrev_b32_e32 v12, 16, v78
	s_waitcnt lgkmcnt(1)
	v_lshlrev_b32_e32 v8, 16, v0
	v_and_b32_e32 v9, 0xffff0000, v0
	v_pk_mul_f32 v[8:9], v[10:11], v[8:9]
	v_lshlrev_b32_e32 v0, 16, v1
	v_and_b32_e32 v1, 0xffff0000, v1
	v_lshlrev_b32_e32 v10, 16, v77
	v_and_b32_e32 v11, 0xffff0000, v77
	v_pk_mul_f32 v[10:11], v[10:11], v[0:1]
	v_lshlrev_b32_e32 v0, 16, v2
	v_and_b32_e32 v1, 0xffff0000, v2
	v_and_b32_e32 v13, 0xffff0000, v78
	v_pk_mul_f32 v[12:13], v[12:13], v[0:1]
	v_lshlrev_b32_e32 v0, 16, v3
	v_and_b32_e32 v1, 0xffff0000, v3
	v_lshlrev_b32_e32 v2, 16, v79
	v_and_b32_e32 v3, 0xffff0000, v79
	v_pk_mul_f32 v[14:15], v[2:3], v[0:1]
	v_cvt_pk_bf16_f32 v0, v8, v9
	v_lshlrev_b64 v[8:9], 11, v[126:127]
	v_lshl_add_u64 v[8:9], s[46:47], 0, v[8:9]
	v_lshl_add_u64 v[8:9], v[8:9], 0, s[52:53]
	v_cvt_pk_bf16_f32 v1, v10, v11
	v_cvt_pk_bf16_f32 v2, v12, v13
	v_cvt_pk_bf16_f32 v3, v14, v15
	v_lshl_add_u64 v[8:9], v[8:9], 0, v[124:125]
	global_store_dwordx4 v[8:9], v[0:3], off offset:1024 sc1
	v_lshlrev_b32_e32 v8, 16, v74
	v_and_b32_e32 v9, 0xffff0000, v74
	s_waitcnt lgkmcnt(0)
	v_lshlrev_b32_e32 v0, 16, v4
	v_and_b32_e32 v1, 0xffff0000, v4
	v_lshlrev_b32_e32 v2, 16, v72
	v_and_b32_e32 v3, 0xffff0000, v72
	v_pk_mul_f32 v[0:1], v[2:3], v[0:1]
	v_lshlrev_b32_e32 v2, 16, v5
	v_and_b32_e32 v3, 0xffff0000, v5
	v_lshlrev_b32_e32 v4, 16, v73
	v_and_b32_e32 v5, 0xffff0000, v73
	v_pk_mul_f32 v[2:3], v[4:5], v[2:3]
	v_lshlrev_b32_e32 v4, 16, v6
	v_and_b32_e32 v5, 0xffff0000, v6
	v_pk_mul_f32 v[4:5], v[8:9], v[4:5]
	v_lshlrev_b32_e32 v6, 16, v7
	v_and_b32_e32 v7, 0xffff0000, v7
	v_lshlrev_b32_e32 v8, 16, v75
	v_and_b32_e32 v9, 0xffff0000, v75
	v_pk_mul_f32 v[6:7], v[8:9], v[6:7]
	v_or_b32_e32 v8, s73, v114
	v_ashrrev_i32_e32 v9, 31, v8
	v_cvt_pk_bf16_f32 v0, v0, v1
	v_cvt_pk_bf16_f32 v1, v2, v3
	v_cvt_pk_bf16_f32 v2, v4, v5
	v_lshlrev_b64 v[4:5], 11, v[8:9]
	v_cvt_pk_bf16_f32 v3, v6, v7
	v_lshl_add_u64 v[8:9], s[46:47], 0, v[4:5]
	ds_read_b128 v[4:7], v106
	v_lshl_add_u64 v[8:9], v[8:9], 0, s[52:53]
	v_lshl_add_u64 v[8:9], v[8:9], 0, v[124:125]
	global_store_dwordx4 v[8:9], v[0:3], off offset:1024 sc1
	ds_read_b128 v[0:3], v107
	s_waitcnt lgkmcnt(1)
	v_lshlrev_b32_e32 v8, 16, v4
	v_and_b32_e32 v9, 0xffff0000, v4
	v_lshlrev_b32_e32 v10, 16, v68
	v_and_b32_e32 v11, 0xffff0000, v68
	v_pk_mul_f32 v[8:9], v[10:11], v[8:9]
	v_lshlrev_b32_e32 v4, 16, v5
	v_and_b32_e32 v5, 0xffff0000, v5
	v_lshlrev_b32_e32 v10, 16, v69
	v_and_b32_e32 v11, 0xffff0000, v69
	v_pk_mul_f32 v[10:11], v[10:11], v[4:5]
	v_lshlrev_b32_e32 v4, 16, v6
	v_and_b32_e32 v5, 0xffff0000, v6
	v_lshlrev_b32_e32 v12, 16, v70
	v_and_b32_e32 v13, 0xffff0000, v70
	v_or_b32_e32 v16, s73, v104
	v_pk_mul_f32 v[12:13], v[12:13], v[4:5]
	v_lshlrev_b32_e32 v4, 16, v7
	v_and_b32_e32 v5, 0xffff0000, v7
	v_lshlrev_b32_e32 v6, 16, v71
	v_and_b32_e32 v7, 0xffff0000, v71
	v_ashrrev_i32_e32 v17, 31, v16
	v_pk_mul_f32 v[14:15], v[6:7], v[4:5]
	v_cvt_pk_bf16_f32 v4, v8, v9
	v_lshlrev_b64 v[8:9], 11, v[16:17]
	v_lshl_add_u64 v[8:9], s[46:47], 0, v[8:9]
	v_lshl_add_u64 v[8:9], v[8:9], 0, s[52:53]
	v_cvt_pk_bf16_f32 v5, v10, v11
	v_cvt_pk_bf16_f32 v6, v12, v13
	v_cvt_pk_bf16_f32 v7, v14, v15
	v_lshl_add_u64 v[8:9], v[8:9], 0, v[124:125]
	global_store_dwordx4 v[8:9], v[4:7], off offset:1024 sc1
	v_lshlrev_b32_e32 v8, 16, v66
	v_and_b32_e32 v9, 0xffff0000, v66
	s_waitcnt lgkmcnt(0)
	v_lshlrev_b32_e32 v4, 16, v0
	v_and_b32_e32 v5, 0xffff0000, v0
	v_lshlrev_b32_e32 v6, 16, v64
	v_and_b32_e32 v7, 0xffff0000, v64
	v_pk_mul_f32 v[4:5], v[6:7], v[4:5]
	v_lshlrev_b32_e32 v0, 16, v1
	v_and_b32_e32 v1, 0xffff0000, v1
	v_lshlrev_b32_e32 v6, 16, v65
	v_and_b32_e32 v7, 0xffff0000, v65
	v_pk_mul_f32 v[6:7], v[6:7], v[0:1]
	v_lshlrev_b32_e32 v0, 16, v2
	v_and_b32_e32 v1, 0xffff0000, v2
	v_or_b32_e32 v12, s73, v105
	v_pk_mul_f32 v[8:9], v[8:9], v[0:1]
	v_lshlrev_b32_e32 v0, 16, v3
	v_and_b32_e32 v1, 0xffff0000, v3
	v_lshlrev_b32_e32 v2, 16, v67
	v_and_b32_e32 v3, 0xffff0000, v67
	v_ashrrev_i32_e32 v13, 31, v12
	v_pk_mul_f32 v[10:11], v[2:3], v[0:1]
	v_cvt_pk_bf16_f32 v0, v4, v5
	v_lshlrev_b64 v[4:5], 11, v[12:13]
	v_lshl_add_u64 v[4:5], s[46:47], 0, v[4:5]
	v_lshl_add_u64 v[4:5], v[4:5], 0, s[52:53]
	v_cvt_pk_bf16_f32 v1, v6, v7
	v_cvt_pk_bf16_f32 v2, v8, v9
	v_cvt_pk_bf16_f32 v3, v10, v11
	v_lshl_add_u64 v[4:5], v[4:5], 0, v[124:125]
	global_store_dwordx4 v[4:5], v[0:3], off offset:1024 sc1
	s_waitcnt lgkmcnt(0)
	s_mov_b64 s[26:27], 0x1000
	s_barrier
	s_cbranch_scc1 .LBB0_444

; #define LAS __attribute__((address_space(3)))
; __device__ __forceinline__ u32x4 pack8(const float (&f)[8]) { u32x4 w; w.x = pk_bf16(f[0], f[1]); w.y = pk_bf16(f[2], f[3]); w.z = pk_bf16(f[4], f[5]); w.w = pk_bf16(f[6], f[7]); return w; }
; __device__ __forceinline__ void attn_prompt_item(const Args& a, int l, int item, LAS unsigned char* lds, int tid, int lane, int wave) {
;     ...
; #pragma unroll
;     for (int pass = 0; pass < 4; ++pass) {
;         const int j = pass * 64 + rl; const int pos = 128 * (b - 1) + j; const int posc = pos < 0 ? 0 : pos;
;         const u32x4 kw = kws[pass], vw = vws[pass];
;         float kf[8]; unpack8(kw, kf);
;         normrope8(kf, sub, kg, tab + (size_t)posc * 16);
;         *(LAS u32x4*)(Kl + j * 144 + sub * 16) = pack8(kf);
;         *(LAS u32x4*)(Vl + (sub >> 2) * 16384 + j * 64 + (sub & 3) * 16) = vw;
;         if (b == 31 && j >= 128) {
;             float* okp = a.out + O_KP + (((size_t)(l * NPB + n) * 128 + (j - 128)) * 2 + kvh) * 64 + sub * 8;
;             float* ovp = a.out + O_VP + (((size_t)(l * NPB + n) * 128 + (j - 128)) * 2 + kvh) * 64 + sub * 8;
;             float vf[8]; unpack8(vw, vf);
;             *(f32x4*)okp = (f32x4){kf[0], kf[1], kf[2], kf[3]}; *(f32x4*)(okp + 4) = (f32x4){kf[4], kf[5], kf[6], kf[7]};
;             *(f32x4*)ovp = (f32x4){vf[0], vf[1], vf[2], vf[3]}; *(f32x4*)(ovp + 4) = (f32x4){vf[4], vf[5], vf[6], vf[7]};
;         }
.LBB0_461:
	s_or_b64 exec, exec, s[8:9]
	s_lshl_b32 s86, s10, 6
	s_waitcnt lgkmcnt(1)
	v_mov_b32_e32 v63, v173
	v_lshlrev_b32_e32 v121, 3, v61
	s_waitcnt lgkmcnt(0)
	v_lshl_add_u64 v[114:115], s[98:99], 0, v[62:63]
	v_lshl_add_u32 v62, v61, 4, 0
	v_lshlrev_b32_e32 v61, 12, v61
	v_lshlrev_b32_e32 v63, 4, v131
	s_cmp_eq_u32 s7, 31
	v_and_b32_e32 v61, 0x4000, v61
	v_and_b32_e32 v63, 48, v63
	s_cselect_b64 s[10:11], -1, 0
	s_add_i32 s8, s4, s72
	s_movk_i32 s4, 0x7f
	v_add3_u32 v119, 0, v61, v63
	v_mul_lo_u32 v61, v60, s84
	v_cmp_lt_i32_e64 s[4:5], s4, v60
	s_ashr_i32 s9, s8, 31
	v_cvt_pk_bf16_f32 v136, v56, v57
	v_cvt_pk_bf16_f32 v137, v58, v59
	v_cvt_pk_bf16_f32 v138, v52, v53
	v_cvt_pk_bf16_f32 v139, v54, v55
	v_add_u32_e32 v120, v62, v61
	v_lshl_add_u32 v61, v60, 6, v119
	s_and_b64 s[14:15], s[10:11], s[4:5]
	v_lshlrev_b32_e32 v62, 2, v121
	ds_write_b128 v120, v[136:139]
	ds_write_b128 v61, v[48:51] offset:36864
	s_and_saveexec_b64 s[4:5], s[14:15]
	s_cbranch_execz .LBB0_463
	v_add_u32_e32 v172, 0xffffff80, v60
	s_lshl_b64 s[14:15], s[8:9], 14
	v_lshlrev_b64 v[40:41], 7, v[172:173]
	s_or_b64 s[14:15], s[14:15], s[86:87]
	v_lshl_add_u64 v[40:41], s[14:15], 0, v[40:41]
	v_lshlrev_b64 v[40:41], 2, v[40:41]
	v_lshl_add_u64 v[42:43], s[50:51], 0, v[40:41]
	v_mov_b32_e32 v63, v173
	v_lshl_add_u64 v[122:123], v[42:43], 0, v[62:63]
	v_lshl_add_u64 v[40:41], s[40:41], 0, v[40:41]
	v_lshl_add_u64 v[136:137], v[40:41], 0, v[62:63]
	v_lshlrev_b32_e32 v40, 16, v48
	v_and_b32_e32 v41, 0xffff0000, v48
	v_lshlrev_b32_e32 v42, 16, v49
	v_and_b32_e32 v43, 0xffff0000, v49
	v_lshlrev_b32_e32 v44, 16, v50
	v_and_b32_e32 v45, 0xffff0000, v50
	v_lshlrev_b32_e32 v46, 16, v51
	v_and_b32_e32 v47, 0xffff0000, v51
	global_store_dwordx4 v[122:123], v[56:59], off sc1
	global_store_dwordx4 v[122:123], v[52:55], off offset:16 sc1
	global_store_dwordx4 v[136:137], v[40:43], off sc1
	global_store_dwordx4 v[136:137], v[44:47], off offset:16 sc1
	global_load_dwordx4 v[44:47], v[114:115], off
	s_nop 0
	global_load_dwordx4 v[40:43], v[114:115], off offset:16

; #define LAS __attribute__((address_space(3)))
; __device__ __forceinline__ u32x4 pack8(const float (&f)[8]) { u32x4 w; w.x = pk_bf16(f[0], f[1]); w.y = pk_bf16(f[2], f[3]); w.z = pk_bf16(f[4], f[5]); w.w = pk_bf16(f[6], f[7]); return w; }
; __device__ __forceinline__ void attn_prompt_item(const Args& a, int l, int item, LAS unsigned char* lds, int tid, int lane, int wave) {
;     ...
; #pragma unroll
;     for (int pass = 0; pass < 4; ++pass) {
;         const int j = pass * 64 + rl; const int pos = 128 * (b - 1) + j; const int posc = pos < 0 ? 0 : pos;
;         const u32x4 kw = kws[pass], vw = vws[pass];
;         float kf[8]; unpack8(kw, kf);
;         normrope8(kf, sub, kg, tab + (size_t)posc * 16);
;         *(LAS u32x4*)(Kl + j * 144 + sub * 16) = pack8(kf);
;         *(LAS u32x4*)(Vl + (sub >> 2) * 16384 + j * 64 + (sub & 3) * 16) = vw;
;         if (b == 31 && j >= 128) {
;             float* okp = a.out + O_KP + (((size_t)(l * NPB + n) * 128 + (j - 128)) * 2 + kvh) * 64 + sub * 8;
;             float* ovp = a.out + O_VP + (((size_t)(l * NPB + n) * 128 + (j - 128)) * 2 + kvh) * 64 + sub * 8;
;             float vf[8]; unpack8(vw, vf);
;             *(f32x4*)okp = (f32x4){kf[0], kf[1], kf[2], kf[3]}; *(f32x4*)(okp + 4) = (f32x4){kf[4], kf[5], kf[6], kf[7]};
;             *(f32x4*)ovp = (f32x4){vf[0], vf[1], vf[2], vf[3]}; *(f32x4*)(ovp + 4) = (f32x4){vf[4], vf[5], vf[6], vf[7]};
;         }
.LBB0_465:
	s_or_b64 exec, exec, s[4:5]
	s_waitcnt lgkmcnt(1)
	v_cvt_pk_bf16_f32 v40, v44, v45
	s_waitcnt lgkmcnt(0)
	v_cvt_pk_bf16_f32 v41, v46, v47
	v_cvt_pk_bf16_f32 v42, v36, v37
	v_cvt_pk_bf16_f32 v43, v38, v39
	v_cmp_lt_i32_e64 s[4:5], 63, v60
	ds_write_b128 v120, v[40:43] offset:9216
	v_lshl_add_u32 v40, v48, 6, v119
	s_and_b64 s[14:15], s[10:11], s[4:5]
	ds_write_b128 v40, v[28:31] offset:36864
	s_and_saveexec_b64 s[4:5], s[14:15]
	s_cbranch_execz .LBB0_467
	v_subrev_u32_e32 v172, 64, v60
	s_lshl_b64 s[14:15], s[8:9], 14
	v_lshlrev_b64 v[40:41], 7, v[172:173]
	s_or_b64 s[14:15], s[14:15], s[86:87]
	v_lshl_add_u64 v[40:41], s[14:15], 0, v[40:41]
	v_lshlrev_b64 v[40:41], 2, v[40:41]
	v_lshl_add_u64 v[42:43], s[50:51], 0, v[40:41]
	v_mov_b32_e32 v63, v173
	v_lshl_add_u64 v[50:51], v[42:43], 0, v[62:63]
	v_lshl_add_u64 v[40:41], s[40:41], 0, v[40:41]
	v_lshl_add_u64 v[52:53], v[40:41], 0, v[62:63]
	v_lshlrev_b32_e32 v40, 16, v28
	v_and_b32_e32 v41, 0xffff0000, v28
	v_lshlrev_b32_e32 v42, 16, v29
	v_and_b32_e32 v43, 0xffff0000, v29
	v_lshlrev_b32_e32 v28, 16, v30
	v_and_b32_e32 v29, 0xffff0000, v30
	v_lshlrev_b32_e32 v30, 16, v31
	v_and_b32_e32 v31, 0xffff0000, v31
	global_store_dwordx4 v[50:51], v[44:47], off sc1
	global_store_dwordx4 v[50:51], v[36:39], off offset:16 sc1
	global_store_dwordx4 v[52:53], v[40:43], off sc1
	global_store_dwordx4 v[52:53], v[28:31], off offset:16 sc1

; #define LAS __attribute__((address_space(3)))
; __device__ __forceinline__ u32x4 pack8(const float (&f)[8]) { u32x4 w; w.x = pk_bf16(f[0], f[1]); w.y = pk_bf16(f[2], f[3]); w.z = pk_bf16(f[4], f[5]); w.w = pk_bf16(f[6], f[7]); return w; }
; __device__ __forceinline__ void attn_prompt_item(const Args& a, int l, int item, LAS unsigned char* lds, int tid, int lane, int wave) {
;     ...
; #pragma unroll
;     for (int pass = 0; pass < 4; ++pass) {
;         const int j = pass * 64 + rl; const int pos = 128 * (b - 1) + j; const int posc = pos < 0 ? 0 : pos;
;         const u32x4 kw = kws[pass], vw = vws[pass];
;         float kf[8]; unpack8(kw, kf);
;         normrope8(kf, sub, kg, tab + (size_t)posc * 16);
;         *(LAS u32x4*)(Kl + j * 144 + sub * 16) = pack8(kf);
;         *(LAS u32x4*)(Vl + (sub >> 2) * 16384 + j * 64 + (sub & 3) * 16) = vw;
;         if (b == 31 && j >= 128) {
;             float* okp = a.out + O_KP + (((size_t)(l * NPB + n) * 128 + (j - 128)) * 2 + kvh) * 64 + sub * 8;
;             float* ovp = a.out + O_VP + (((size_t)(l * NPB + n) * 128 + (j - 128)) * 2 + kvh) * 64 + sub * 8;
;             float vf[8]; unpack8(vw, vf);
;             *(f32x4*)okp = (f32x4){kf[0], kf[1], kf[2], kf[3]}; *(f32x4*)(okp + 4) = (f32x4){kf[4], kf[5], kf[6], kf[7]};
;             *(f32x4*)ovp = (f32x4){vf[0], vf[1], vf[2], vf[3]}; *(f32x4*)(ovp + 4) = (f32x4){vf[4], vf[5], vf[6], vf[7]};
;         }
.LBB0_469:
	s_or_b64 exec, exec, s[4:5]
	v_cmp_lt_i32_e64 s[4:5], -1, v60
	s_waitcnt lgkmcnt(1)
	v_cvt_pk_bf16_f32 v44, v36, v37
	s_waitcnt lgkmcnt(0)
	v_cvt_pk_bf16_f32 v45, v38, v39
	v_cvt_pk_bf16_f32 v46, v40, v41
	v_cvt_pk_bf16_f32 v47, v42, v43
	s_and_b64 s[14:15], s[10:11], s[4:5]
	ds_write_b128 v120, v[44:47] offset:18432
	ds_write_b128 v61, v[24:27] offset:45056
	s_and_saveexec_b64 s[4:5], s[14:15]
	s_cbranch_execz .LBB0_471
	v_mov_b32_e32 v61, v173
	s_lshl_b64 s[14:15], s[8:9], 14
	v_lshlrev_b64 v[28:29], 7, v[60:61]
	s_or_b64 s[14:15], s[14:15], s[86:87]
	v_lshl_add_u64 v[28:29], s[14:15], 0, v[28:29]
	v_lshlrev_b64 v[28:29], 2, v[28:29]
	v_lshl_add_u64 v[30:31], s[50:51], 0, v[28:29]
	v_mov_b32_e32 v63, v173
	v_lshl_add_u64 v[32:33], v[30:31], 0, v[62:63]
	v_lshl_add_u64 v[28:29], s[40:41], 0, v[28:29]
	v_lshl_add_u64 v[34:35], v[28:29], 0, v[62:63]
	v_lshlrev_b32_e32 v28, 16, v24
	v_and_b32_e32 v29, 0xffff0000, v24
	v_lshlrev_b32_e32 v30, 16, v25
	v_and_b32_e32 v31, 0xffff0000, v25
	v_lshlrev_b32_e32 v24, 16, v26
	v_and_b32_e32 v25, 0xffff0000, v26
	v_lshlrev_b32_e32 v26, 16, v27
	v_and_b32_e32 v27, 0xffff0000, v27
	global_store_dwordx4 v[32:33], v[36:39], off sc1
	global_store_dwordx4 v[32:33], v[40:43], off offset:16 sc1
	global_store_dwordx4 v[34:35], v[28:31], off sc1
	global_store_dwordx4 v[34:35], v[24:27], off offset:16 sc1
	global_load_dwordx4 v[32:35], v[114:115], off
	s_nop 0
	global_load_dwordx4 v[28:31], v[114:115], off offset:16

; #define LAS __attribute__((address_space(3)))
; __device__ __forceinline__ u32x4 pack8(const float (&f)[8]) { u32x4 w; w.x = pk_bf16(f[0], f[1]); w.y = pk_bf16(f[2], f[3]); w.z = pk_bf16(f[4], f[5]); w.w = pk_bf16(f[6], f[7]); return w; }
; __device__ __forceinline__ void attn_prompt_item(const Args& a, int l, int item, LAS unsigned char* lds, int tid, int lane, int wave) {
;     ...
; #pragma unroll
;     for (int pass = 0; pass < 4; ++pass) {
;         const int j = pass * 64 + rl; const int pos = 128 * (b - 1) + j; const int posc = pos < 0 ? 0 : pos;
;         const u32x4 kw = kws[pass], vw = vws[pass];
;         float kf[8]; unpack8(kw, kf);
;         normrope8(kf, sub, kg, tab + (size_t)posc * 16);
;         *(LAS u32x4*)(Kl + j * 144 + sub * 16) = pack8(kf);
;         *(LAS u32x4*)(Vl + (sub >> 2) * 16384 + j * 64 + (sub & 3) * 16) = vw;
;         if (b == 31 && j >= 128) {
;             float* okp = a.out + O_KP + (((size_t)(l * NPB + n) * 128 + (j - 128)) * 2 + kvh) * 64 + sub * 8;
;             float* ovp = a.out + O_VP + (((size_t)(l * NPB + n) * 128 + (j - 128)) * 2 + kvh) * 64 + sub * 8;
;             float vf[8]; unpack8(vw, vf);
;             *(f32x4*)okp = (f32x4){kf[0], kf[1], kf[2], kf[3]}; *(f32x4*)(okp + 4) = (f32x4){kf[4], kf[5], kf[6], kf[7]};
;             *(f32x4*)ovp = (f32x4){vf[0], vf[1], vf[2], vf[3]}; *(f32x4*)(ovp + 4) = (f32x4){vf[4], vf[5], vf[6], vf[7]};
;         }
.LBB0_473:
	s_or_b64 exec, exec, s[4:5]
	s_movk_i32 s0, 0xffbf
	v_cmp_lt_i32_e32 vcc, s0, v60
	s_waitcnt lgkmcnt(0)
	v_cvt_pk_bf16_f32 v30, v24, v25
	v_cvt_pk_bf16_f32 v31, v26, v27
	v_cvt_pk_bf16_f32 v32, v20, v21
	v_cvt_pk_bf16_f32 v33, v22, v23
	v_lshl_add_u32 v28, v28, 6, v119
	s_and_b64 s[4:5], s[10:11], vcc
	ds_write_b128 v120, v[30:33] offset:27648
	ds_write_b128 v28, v[16:19] offset:36864
	s_and_saveexec_b64 s[0:1], s[4:5]
	s_cbranch_execz .LBB0_475
	v_mov_b32_e32 v49, v173
	s_lshl_b64 s[4:5], s[8:9], 14
	v_lshlrev_b64 v[28:29], 7, v[48:49]
	s_or_b64 s[4:5], s[4:5], s[86:87]
	v_lshl_add_u64 v[28:29], s[4:5], 0, v[28:29]
	v_lshlrev_b64 v[28:29], 2, v[28:29]
	v_lshl_add_u64 v[30:31], s[50:51], 0, v[28:29]
	v_mov_b32_e32 v63, v173
	v_lshl_add_u64 v[32:33], v[30:31], 0, v[62:63]
	v_lshl_add_u64 v[28:29], s[40:41], 0, v[28:29]
	v_lshl_add_u64 v[34:35], v[28:29], 0, v[62:63]
	v_lshlrev_b32_e32 v28, 16, v16
	v_and_b32_e32 v29, 0xffff0000, v16
	v_lshlrev_b32_e32 v30, 16, v17
	v_and_b32_e32 v31, 0xffff0000, v17
	v_lshlrev_b32_e32 v16, 16, v18
	v_and_b32_e32 v17, 0xffff0000, v18
	v_lshlrev_b32_e32 v18, 16, v19
	v_and_b32_e32 v19, 0xffff0000, v19
	global_store_dwordx4 v[32:33], v[24:27], off sc1
	global_store_dwordx4 v[32:33], v[20:23], off offset:16 sc1
	global_store_dwordx4 v[34:35], v[28:31], off sc1
	global_store_dwordx4 v[34:35], v[16:19], off offset:16 sc1

; #define LAS __attribute__((address_space(3)))
; __device__ __forceinline__ int crow(int r, int hi) { return (r & 3) + 8 * (r >> 2) + 4 * hi; }
; __device__ __forceinline__ s16x4 vtr(const LAS unsigned char* p) { return __builtin_bit_cast(s16x4, __builtin_amdgcn_ds_read_tr16_b64_v4i16((LAS v4i16_t*)p)); }
; template <bool SAMPLE> ...
;     ...
;     u32x4 pw[5][2];
; #pragma unroll
;     for (int t = 0; t < 5; ++t) {
; #pragma unroll
;         for (int i = 0; i < 16; ++i) { p[t][i] = __builtin_amdgcn_exp2f(p[t][i] - mx); lsum += p[t][i]; }
; #pragma unroll
;         for (int s = 0; s < 2; ++s) { pw[t][s].x = pk_bf16(p[t][8 * s + 0], p[t][8 * s + 1]); pw[t][s].y = pk_bf16(p[t][8 * s + 2], p[t][8 * s + 3]); pw[t][s].z = pk_bf16(p[t][8 * s + 4], p[t][8 * s + 5]); pw[t][s].w = pk_bf16(p[t][8 * s + 6], p[t][8 * s + 7]); }
;     }
;     lsum += __shfl_xor(lsum, 32);
;     const float denom = lsum + __builtin_amdgcn_exp2f(sk - mx);
;     if (hi == 0) wsf[r32] = 1.0f / denom;
;     __builtin_amdgcn_sched_barrier(0);
;     f32x16 o[2];
; #pragma unroll
;     for (int d0 = 0; d0 < 2; ++d0)
; #pragma unroll
;         for (int i = 0; i < 16; ++i) o[d0][i] = 0.f;
;     const int i16 = lane & 15;
;     const LAS unsigned char* vb = Vl + (4 * hi + (i16 >> 2)) * 64 + ((lane >> 4) & 1) * 32 + (i16 & 3) * 8;
; #pragma unroll
;     for (int t = 0; t < 5; ++t)
; #pragma unroll
;         for (int s = 0; s < 2; ++s) {
;             const bf16x8 pa = __builtin_bit_cast(bf16x8, pw[t][s]);
; #pragma unroll
;             for (int d0 = 0; d0 < 2; ++d0) {
;                 const s16x4 vlo = vtr(vb + d0 * vhalf + (32 * t + 16 * s) * 64), vhi = vtr(vb + d0 * vhalf + (32 * t + 16 * s + 8) * 64);
;                 const bf16x8 vf = (bf16x8){vlo[0], vlo[1], vlo[2], vlo[3], vhi[0], vhi[1], vhi[2], vhi[3]};
;                 o[d0] = __builtin_amdgcn_mfma_f32_32x32x16_bf16(pa, vf, o[d0], 0, 0, 0);
;             }
;         }
;     __builtin_amdgcn_sched_barrier(0);
;     asm volatile("s_waitcnt lgkmcnt(0)" ::: "memory");
; #pragma unroll
;     for (int i = 0; i < 16; ++i) {
;         const int qq = crow(i, hi);
;         const float rl = wsf[qq];
; #pragma unroll
;         for (int d0 = 0; d0 < 2; ++d0) ost[qq * 64 + d0 * 32 + r32] = (bf16_t)(pk_bf16(o[d0][i] * rl, 0.f) & 0xffffu);
.LBB0_487:
	s_or_b64 exec, exec, s[94:95]
	v_lshl_add_u64 v[48:49], s[62:63], 0, v[172:173]
	v_cvt_pk_bf16_f32 v32, v32, v33
	v_cvt_pk_bf16_f32 v33, v34, v35
	v_cvt_pk_bf16_f32 v34, v141, v142
	v_cvt_pk_bf16_f32 v35, v143, v144
	v_cvt_pk_bf16_f32 v36, v36, v37
	v_cvt_pk_bf16_f32 v37, v38, v39
	v_cvt_pk_bf16_f32 v38, v137, v138
	v_cvt_pk_bf16_f32 v39, v139, v140
	v_cvt_pk_bf16_f32 v40, v40, v41
	v_cvt_pk_bf16_f32 v41, v42, v43
	v_cvt_pk_bf16_f32 v43, v46, v47
	v_cvt_pk_bf16_f32 v46, v120, v121
	v_cvt_pk_bf16_f32 v47, v122, v123
	v_cvt_pk_bf16_f32 v120, v24, v25
	v_cvt_pk_bf16_f32 v121, v26, v27
	v_cvt_pk_bf16_f32 v122, v28, v29
	v_cvt_pk_bf16_f32 v123, v30, v31
	v_cvt_pk_bf16_f32 v138, v16, v17
	v_cvt_pk_bf16_f32 v139, v18, v19
	v_cvt_pk_bf16_f32 v140, v20, v21
	v_cvt_pk_bf16_f32 v141, v22, v23
	v_cvt_pk_bf16_f32 v142, v8, v9
	v_cvt_pk_bf16_f32 v143, v10, v11
	v_cvt_pk_bf16_f32 v144, v12, v13
	v_cvt_pk_bf16_f32 v145, v14, v15
	s_waitcnt lgkmcnt(0)
	v_ashrrev_i32_e32 v129, 31, v128
	v_mul_u32_u24_e32 v52, 0x90, v134
	v_lshrrev_b32_e32 v154, 2, v132
	v_cvt_pk_bf16_f32 v42, v44, v45
	v_cvt_pk_bf16_f32 v44, v116, v117
	v_cvt_pk_bf16_f32 v45, v118, v119
	v_cvt_pk_bf16_f32 v150, v0, v1
	v_cvt_pk_bf16_f32 v151, v2, v3
	v_cvt_pk_bf16_f32 v152, v4, v5
	v_cvt_pk_bf16_f32 v153, v6, v7
	v_cvt_pk_bf16_f32 v60, v59, v60
	v_cvt_pk_bf16_f32 v61, v61, v62
	v_cvt_pk_bf16_f32 v62, v63, v112
	v_cvt_pk_bf16_f32 v63, v114, v115
	v_cvt_pk_bf16_f32 v16, v50, v51
	v_cvt_pk_bf16_f32 v17, v53, v54
	v_cvt_pk_bf16_f32 v18, v55, v56
	v_cvt_pk_bf16_f32 v19, v57, v58
	v_and_or_b32 v0, v154, 3, v136
	v_lshlrev_b32_e32 v115, 6, v0
	v_lshlrev_b32_e32 v1, 1, v132
	v_add_u32_e32 v0, s60, v115
	v_and_b32_e32 v117, 32, v1
	v_and_b32_e32 v118, 24, v135
	v_add3_u32 v50, v0, v117, v118
	ds_read_b64_tr_b16 v[0:1], v50 offset:36864
	ds_read_b64_tr_b16 v[2:3], v50 offset:37376
	ds_read_b64_tr_b16 v[20:21], v50 offset:53248
	ds_read_b64_tr_b16 v[22:23], v50 offset:53760
	s_waitcnt lgkmcnt(2)
	v_mfma_f32_32x32x16_bf16 v[0:15], v[16:19], v[0:3], 0
	ds_read_b64_tr_b16 v[54:55], v50 offset:37888
	ds_read_b64_tr_b16 v[56:57], v50 offset:38400
	s_waitcnt lgkmcnt(2)
	v_mfma_f32_32x32x16_bf16 v[16:31], v[16:19], v[20:23], 0
	s_waitcnt lgkmcnt(0)
	v_mfma_f32_32x32x16_bf16 v[0:15], v[60:63], v[54:57], v[0:15]
	ds_read_b64_tr_b16 v[54:55], v50 offset:54272
	ds_read_b64_tr_b16 v[56:57], v50 offset:54784
	s_waitcnt lgkmcnt(0)
	v_mfma_f32_32x32x16_bf16 v[16:31], v[60:63], v[54:57], v[16:31]
	ds_read_b64_tr_b16 v[54:55], v50 offset:38912
	ds_read_b64_tr_b16 v[56:57], v50 offset:39424
	s_waitcnt lgkmcnt(0)
	v_mfma_f32_32x32x16_bf16 v[0:15], v[150:153], v[54:57], v[0:15]
	ds_read_b64_tr_b16 v[54:55], v50 offset:55296
	ds_read_b64_tr_b16 v[56:57], v50 offset:55808
	s_waitcnt lgkmcnt(0)
	v_mfma_f32_32x32x16_bf16 v[16:31], v[150:153], v[54:57], v[16:31]
	ds_read_b64_tr_b16 v[54:55], v50 offset:39936
	ds_read_b64_tr_b16 v[56:57], v50 offset:40448
	s_waitcnt lgkmcnt(0)
	v_mfma_f32_32x32x16_bf16 v[0:15], v[142:145], v[54:57], v[0:15]
	ds_read_b64_tr_b16 v[54:55], v50 offset:56320
	ds_read_b64_tr_b16 v[56:57], v50 offset:56832
	s_waitcnt lgkmcnt(0)
	v_mfma_f32_32x32x16_bf16 v[16:31], v[142:145], v[54:57], v[16:31]
	ds_read_b64_tr_b16 v[54:55], v50 offset:40960
	ds_read_b64_tr_b16 v[56:57], v50 offset:41472
	s_waitcnt lgkmcnt(0)
	v_mfma_f32_32x32x16_bf16 v[0:15], v[138:141], v[54:57], v[0:15]
	ds_read_b64_tr_b16 v[54:55], v50 offset:57344
	ds_read_b64_tr_b16 v[56:57], v50 offset:57856
	s_waitcnt lgkmcnt(0)
	v_mfma_f32_32x32x16_bf16 v[16:31], v[138:141], v[54:57], v[16:31]
	ds_read_b64_tr_b16 v[54:55], v50 offset:41984
	ds_read_b64_tr_b16 v[56:57], v50 offset:42496
	s_waitcnt lgkmcnt(0)
	v_mfma_f32_32x32x16_bf16 v[0:15], v[120:123], v[54:57], v[0:15]
	ds_read_b64_tr_b16 v[54:55], v50 offset:58368
	ds_read_b64_tr_b16 v[56:57], v50 offset:58880
	s_waitcnt lgkmcnt(0)
	v_mfma_f32_32x32x16_bf16 v[16:31], v[120:123], v[54:57], v[16:31]
	ds_read_b64_tr_b16 v[54:55], v50 offset:43008
	ds_read_b64_tr_b16 v[56:57], v50 offset:43520
	s_waitcnt lgkmcnt(0)
	v_mfma_f32_32x32x16_bf16 v[0:15], v[44:47], v[54:57], v[0:15]
	ds_read_b64_tr_b16 v[54:55], v50 offset:59392
	ds_read_b64_tr_b16 v[56:57], v50 offset:59904
	s_waitcnt lgkmcnt(0)
	v_mfma_f32_32x32x16_bf16 v[16:31], v[44:47], v[54:57], v[16:31]
	ds_read_b64_tr_b16 v[44:45], v50 offset:44032
	ds_read_b64_tr_b16 v[46:47], v50 offset:44544
	s_waitcnt lgkmcnt(0)
	v_mfma_f32_32x32x16_bf16 v[0:15], v[40:43], v[44:47], v[0:15]
	ds_read_b64_tr_b16 v[44:45], v50 offset:60416
	ds_read_b64_tr_b16 v[46:47], v50 offset:60928
	s_waitcnt lgkmcnt(0)
	v_mfma_f32_32x32x16_bf16 v[16:31], v[40:43], v[44:47], v[16:31]
	ds_read_b64_tr_b16 v[40:41], v50 offset:45056
	ds_read_b64_tr_b16 v[42:43], v50 offset:45568
	s_waitcnt lgkmcnt(0)
	v_mfma_f32_32x32x16_bf16 v[0:15], v[36:39], v[40:43], v[0:15]
	ds_read_b64_tr_b16 v[40:41], v50 offset:61440
	ds_read_b64_tr_b16 v[42:43], v50 offset:61952
	s_waitcnt lgkmcnt(0)
	v_mfma_f32_32x32x16_bf16 v[16:31], v[36:39], v[40:43], v[16:31]
	ds_read_b64_tr_b16 v[36:37], v50 offset:46080
	ds_read_b64_tr_b16 v[38:39], v50 offset:46592
	s_waitcnt lgkmcnt(0)
	v_mfma_f32_32x32x16_bf16 v[0:15], v[32:35], v[36:39], v[0:15]
	ds_read_b64_tr_b16 v[36:37], v50 offset:62464
	ds_read_b64_tr_b16 v[38:39], v50 offset:62976
	s_waitcnt lgkmcnt(0)
	v_mfma_f32_32x32x16_bf16 v[16:31], v[32:35], v[36:39], v[16:31]
	s_waitcnt lgkmcnt(0)
	v_lshl_add_u32 v112, v136, 2, s65
	ds_read_b128 v[32:35], v112
	ds_read_b128 v[36:39], v112 offset:32
	v_lshl_add_u32 v40, v134, 1, s64
	v_lshlrev_b32_e32 v41, 9, v125
	v_add_u32_e32 v116, v40, v41
	s_waitcnt lgkmcnt(1)
; #define LAS __attribute__((address_space(3)))
; __device__ __forceinline__ u32x4 pack8(const float (&f)[8]) { u32x4 w; w.x = pk_bf16(f[0], f[1]); w.y = pk_bf16(f[2], f[3]); w.z = pk_bf16(f[4], f[5]); w.w = pk_bf16(f[6], f[7]); return w; }
; __device__ __forceinline__ int crow(int r, int hi) { return (r & 3) + 8 * (r >> 2) + 4 * hi; }
; template <bool SAMPLE> ...
;     ...
; #pragma unroll
;     for (int i = 0; i < 16; ++i) {
;         const int qq = crow(i, hi);
;         const float rl = wsf[qq];
; #pragma unroll
;         for (int d0 = 0; d0 < 2; ++d0) ost[qq * 64 + d0 * 32 + r32] = (bf16_t)(pk_bf16(o[d0][i] * rl, 0.f) & 0xffffu);
;     }
;     asm volatile("s_waitcnt lgkmcnt(0)" ::: "memory");
; #pragma unroll
;     for (int it4 = 0; it4 < 4; ++it4) {
;         const int qq = it4 * 8 + (lane >> 3), ch = lane & 7;
;         const int orow = SAMPLE ? row0 + (qq & 7) : row0 + qq;
;         const int ohead = SAMPLE ? head0 + (qq >> 3) : head0;
;         const u32x4 ow = *(const LAS u32x4*)(ost + qq * 64 + ch * 8);
;         float of[8], zf[8], yv[8];
;         unpack8(ow, of); unpack8(zw[it4], zf);
; #pragma unroll
;         for (int k = 0; k < 8; ++k) yv[k] = of[k] * zf[k];
;         *(u32x4*)(Y + (size_t)orow * D + 512 + ohead * 64 + ch * 8) = pack8(yv);
;     }
	s_nop 0
	v_mul_f32_e32 v0, v0, v32
	v_cvt_pk_bf16_f32 v0, v0, s0
	ds_write_b16 v116, v0
	s_nop 0
	v_mul_f32_e32 v0, v16, v32
	v_cvt_pk_bf16_f32 v0, v0, s0
	v_lshlrev_b32_e32 v16, 7, v136
	ds_write_b16 v116, v0 offset:64
	v_or_b32_e32 v0, 0x80, v16
	v_add_u32_e32 v119, v40, v0
	v_mul_f32_e32 v0, v1, v33
	v_cvt_pk_bf16_f32 v0, v0, s0
	ds_write_b16 v119, v0
	v_mul_f32_e32 v0, v17, v33
	v_cvt_pk_bf16_f32 v0, v0, s0
	ds_write_b16 v119, v0 offset:64
	v_or_b32_e32 v0, 0x100, v16
	v_add_u32_e32 v120, v40, v0
	v_mul_f32_e32 v0, v2, v34
	v_cvt_pk_bf16_f32 v0, v0, s0
	ds_write_b16 v120, v0
	v_mul_f32_e32 v0, v18, v34
	v_cvt_pk_bf16_f32 v0, v0, s0
	ds_write_b16 v120, v0 offset:64
	v_or_b32_e32 v0, 0x180, v16
	v_add_u32_e32 v121, v40, v0
	v_mul_f32_e32 v0, v3, v35
	v_cvt_pk_bf16_f32 v0, v0, s0
	ds_write_b16 v121, v0
	v_mul_f32_e32 v0, v19, v35
	v_cvt_pk_bf16_f32 v0, v0, s0
	ds_write_b16 v121, v0 offset:64
	v_or_b32_e32 v0, 0x400, v16
	v_add_u32_e32 v122, v40, v0
	s_waitcnt lgkmcnt(8)
	v_mul_f32_e32 v0, v4, v36
	v_cvt_pk_bf16_f32 v0, v0, s0
	ds_write_b16 v122, v0
	v_mul_f32_e32 v0, v20, v36
	v_cvt_pk_bf16_f32 v0, v0, s0
	ds_write_b16 v122, v0 offset:64
	v_or_b32_e32 v0, 0x480, v16
	v_add_u32_e32 v123, v40, v0
	v_mul_f32_e32 v0, v5, v37
	v_cvt_pk_bf16_f32 v0, v0, s0
	ds_write_b16 v123, v0
	v_mul_f32_e32 v0, v21, v37
	v_cvt_pk_bf16_f32 v0, v0, s0
	ds_write_b16 v123, v0 offset:64
	v_or_b32_e32 v0, 0x500, v16
	v_add_u32_e32 v135, v40, v0
	v_mul_f32_e32 v0, v6, v38
	v_cvt_pk_bf16_f32 v0, v0, s0
	ds_write_b16 v135, v0
	v_mul_f32_e32 v0, v22, v38
	v_cvt_pk_bf16_f32 v0, v0, s0
	ds_write_b16 v135, v0 offset:64
	v_or_b32_e32 v0, 0x580, v16
	v_add_u32_e32 v134, v40, v0
	v_mul_f32_e32 v0, v7, v39
	v_cvt_pk_bf16_f32 v0, v0, s0
	ds_write_b16 v134, v0
	v_mul_f32_e32 v0, v23, v39
	v_cvt_pk_bf16_f32 v4, v0, s0
	ds_read_b128 v[0:3], v112 offset:64
	ds_write_b16 v134, v4 offset:64
	ds_read_b128 v[4:7], v112 offset:96
	v_or_b32_e32 v17, 0x800, v16
	v_add_u32_e32 v136, v40, v17
	s_waitcnt lgkmcnt(2)
	v_mul_f32_e32 v8, v8, v0
	v_mul_f32_e32 v0, v24, v0
	v_cvt_pk_bf16_f32 v0, v0, s0
	ds_write_b16 v136, v0 offset:64
	v_or_b32_e32 v0, 0x880, v16
	v_add_u32_e32 v137, v40, v0
	v_mul_f32_e32 v0, v9, v1
	v_cvt_pk_bf16_f32 v0, v0, s0
	ds_write_b16 v137, v0
	v_mul_f32_e32 v0, v25, v1
	v_cvt_pk_bf16_f32 v0, v0, s0
	ds_write_b16 v137, v0 offset:64
	v_or_b32_e32 v0, 0x900, v16
	v_add_u32_e32 v138, v40, v0
	v_mul_f32_e32 v0, v10, v2
	v_cvt_pk_bf16_f32 v0, v0, s0
	ds_write_b16 v138, v0
	v_mul_f32_e32 v0, v26, v2
	v_cvt_pk_bf16_f32 v0, v0, s0
	ds_write_b16 v138, v0 offset:64
	v_or_b32_e32 v0, 0x980, v16
	v_add_u32_e32 v139, v40, v0
	v_mul_f32_e32 v0, v11, v3
	v_cvt_pk_bf16_f32 v0, v0, s0
	ds_write_b16 v139, v0
	v_mul_f32_e32 v0, v27, v3
	v_cvt_pk_bf16_f32 v0, v0, s0
	ds_write_b16 v139, v0 offset:64
	v_or_b32_e32 v0, 0xc00, v16
	v_add_u32_e32 v140, v40, v0
	s_waitcnt lgkmcnt(7)
	v_mul_f32_e32 v0, v12, v4
	v_cvt_pk_bf16_f32 v0, v0, s0
	ds_write_b16 v140, v0
	v_mul_f32_e32 v0, v28, v4
	v_cvt_pk_bf16_f32 v0, v0, s0
	ds_write_b16 v140, v0 offset:64
	v_or_b32_e32 v0, 0xc80, v16
	v_add_u32_e32 v141, v40, v0
	v_mul_f32_e32 v0, v13, v5
	v_cvt_pk_bf16_f32 v0, v0, s0
	ds_write_b16 v141, v0
	v_mul_f32_e32 v0, v29, v5
	v_cvt_pk_bf16_f32 v0, v0, s0
	ds_write_b16 v141, v0 offset:64
	v_or_b32_e32 v0, 0xd00, v16
	v_add_u32_e32 v142, v40, v0
	v_mul_f32_e32 v0, v14, v6
	v_cvt_pk_bf16_f32 v0, v0, s0
	ds_write_b16 v142, v0
	v_mul_f32_e32 v0, v30, v6
	v_cvt_pk_bf16_f32 v0, v0, s0
	ds_write_b16 v142, v0 offset:64
	v_or_b32_e32 v0, 0xd80, v16
	v_add_u32_e32 v143, v40, v0
	v_mul_f32_e32 v0, v15, v7
	v_cvt_pk_bf16_f32 v0, v0, s0
	ds_write_b16 v143, v0
	v_mul_f32_e32 v0, v31, v7
	v_cvt_pk_bf16_f32 v8, v8, s0
	v_cvt_pk_bf16_f32 v0, v0, s0
	ds_write_b16 v136, v8
	ds_write_b16 v143, v0 offset:64
	v_add_u32_e32 v16, s64, v124
	v_lshlrev_b32_e32 v0, 7, v133
	s_waitcnt lgkmcnt(0)
	v_add_u32_e32 v144, v16, v0
	ds_read_b128 v[0:3], v144
	v_or_b32_e32 v114, 8, v133
	v_lshlrev_b32_e32 v4, 7, v114
	v_add_u32_e32 v145, v16, v4
	ds_read_b128 v[4:7], v145
	s_waitcnt lgkmcnt(1)
	v_lshlrev_b32_e32 v8, 16, v0
	v_and_b32_e32 v9, 0xffff0000, v0
	v_lshlrev_b32_e32 v10, 16, v108
	v_and_b32_e32 v11, 0xffff0000, v108
	v_pk_mul_f32 v[8:9], v[10:11], v[8:9]
	v_lshlrev_b32_e32 v0, 16, v1
	v_and_b32_e32 v1, 0xffff0000, v1
	v_lshlrev_b32_e32 v10, 16, v109
	v_and_b32_e32 v11, 0xffff0000, v109
	v_pk_mul_f32 v[10:11], v[10:11], v[0:1]
	v_lshlrev_b32_e32 v0, 16, v2
	v_and_b32_e32 v1, 0xffff0000, v2
	v_lshlrev_b32_e32 v12, 16, v110
	v_and_b32_e32 v13, 0xffff0000, v110
	v_pk_mul_f32 v[12:13], v[12:13], v[0:1]
	v_lshlrev_b32_e32 v0, 16, v3
	v_and_b32_e32 v1, 0xffff0000, v3
	v_lshlrev_b32_e32 v2, 16, v111
	v_and_b32_e32 v3, 0xffff0000, v111
	v_pk_mul_f32 v[14:15], v[2:3], v[0:1]
	v_cvt_pk_bf16_f32 v0, v8, v9
	v_lshlrev_b64 v[8:9], 11, v[128:129]
	v_lshl_add_u64 v[8:9], s[46:47], 0, v[8:9]
	v_lshl_add_u64 v[8:9], v[8:9], 0, s[52:53]
	v_mov_b32_e32 v125, v173
	v_cvt_pk_bf16_f32 v1, v10, v11
	v_cvt_pk_bf16_f32 v2, v12, v13
	v_cvt_pk_bf16_f32 v3, v14, v15
	v_lshl_add_u64 v[8:9], v[8:9], 0, v[124:125]
	global_store_dwordx4 v[8:9], v[0:3], off offset:1024 sc1
	v_lshlrev_b32_e32 v8, 16, v106
	v_and_b32_e32 v9, 0xffff0000, v106
	s_waitcnt lgkmcnt(0)
; #define LAS __attribute__((address_space(3)))
; __device__ __forceinline__ u32x4 pack8(const float (&f)[8]) { u32x4 w; w.x = pk_bf16(f[0], f[1]); w.y = pk_bf16(f[2], f[3]); w.z = pk_bf16(f[4], f[5]); w.w = pk_bf16(f[6], f[7]); return w; }
; template <bool SAMPLE> ...
;     ...
;     for (int d0 = 0; d0 < 4; ++d0) unpack8(qw[d0], q[d0]);
;     float ss = 0.f;
; #pragma unroll
;     for (int d0 = 0; d0 < 4; ++d0)
; #pragma unroll
;         for (int i = 0; i < 8; ++i) ss += q[d0][i] * q[d0][i];
;     ss += __shfl_xor(ss, 32);
;     const float rstd = rsqrtf(ss * (1.0f / 64.0f) + EPS);
; #pragma unroll
;     for (int d0 = 0; d0 < 4; ++d0) { const f32x4 g0 = *(const f32x4*)(qg + d0 * 16 + hi * 8), g1 = *(const f32x4*)(qg + d0 * 16 + hi * 8 + 4);
;         q[d0][0] *= rstd * g0.x; q[d0][1] *= rstd * g0.y; q[d0][2] *= rstd * g0.z; q[d0][3] *= rstd * g0.w; q[d0][4] *= rstd * g1.x; q[d0][5] *= rstd * g1.y; q[d0][6] *= rstd * g1.z; q[d0][7] *= rstd * g1.w; }
;     {
;         const float* tr = tab + (size_t)mypos * 16;
;         const f32x4 c0 = *(const f32x4*)(tr), c1 = *(const f32x4*)(tr + 4), s0 = *(const f32x4*)(tr + 8), s1 = *(const f32x4*)(tr + 12);
;     ...
;     for (int it4 = 0; it4 < 4; ++it4) {
;         const int qq = it4 * 8 + (lane >> 3), ch = lane & 7;
;         const int orow = SAMPLE ? row0 + (qq & 7) : row0 + qq;
;         const int ohead = SAMPLE ? head0 + (qq >> 3) : head0;
;         const u32x4 ow = *(const LAS u32x4*)(ost + qq * 64 + ch * 8);
;         float of[8], zf[8], yv[8];
;         unpack8(ow, of); unpack8(zw[it4], zf);
; #pragma unroll
;         for (int k = 0; k < 8; ++k) yv[k] = of[k] * zf[k];
;         *(u32x4*)(Y + (size_t)orow * D + 512 + ohead * 64 + ch * 8) = pack8(yv);
;     }
	v_lshlrev_b32_e32 v0, 16, v4
	v_and_b32_e32 v1, 0xffff0000, v4
	v_lshlrev_b32_e32 v2, 16, v104
	v_and_b32_e32 v3, 0xffff0000, v104
	v_pk_mul_f32 v[0:1], v[2:3], v[0:1]
	v_lshlrev_b32_e32 v2, 16, v5
	v_and_b32_e32 v3, 0xffff0000, v5
	v_lshlrev_b32_e32 v4, 16, v105
	v_and_b32_e32 v5, 0xffff0000, v105
	v_pk_mul_f32 v[2:3], v[4:5], v[2:3]
	v_lshlrev_b32_e32 v4, 16, v6
	v_and_b32_e32 v5, 0xffff0000, v6
	v_pk_mul_f32 v[4:5], v[8:9], v[4:5]
	v_lshlrev_b32_e32 v6, 16, v7
	v_and_b32_e32 v7, 0xffff0000, v7
	v_lshlrev_b32_e32 v8, 16, v107
	v_and_b32_e32 v9, 0xffff0000, v107
	v_pk_mul_f32 v[6:7], v[8:9], v[6:7]
	v_or_b32_e32 v8, s92, v114
	v_ashrrev_i32_e32 v9, 31, v8
	v_cvt_pk_bf16_f32 v0, v0, v1
	v_cvt_pk_bf16_f32 v1, v2, v3
	v_cvt_pk_bf16_f32 v2, v4, v5
	v_lshlrev_b64 v[4:5], 11, v[8:9]
	v_lshl_add_u64 v[4:5], s[46:47], 0, v[4:5]
	v_lshl_add_u64 v[4:5], v[4:5], 0, s[52:53]
	v_cvt_pk_bf16_f32 v3, v6, v7
	v_lshl_add_u64 v[4:5], v[4:5], 0, v[124:125]
	v_or_b32_e32 v104, 16, v133
	global_store_dwordx4 v[4:5], v[0:3], off offset:1024 sc1
	v_or_b32_e32 v105, 24, v133
	v_lshlrev_b32_e32 v4, 7, v105
	v_lshlrev_b32_e32 v0, 7, v104
	v_add_u32_e32 v106, v16, v0
	ds_read_b128 v[0:3], v106
	v_add_u32_e32 v107, v16, v4
	ds_read_b128 v[4:7], v107
	v_lshlrev_b32_e32 v10, 16, v100
	v_and_b32_e32 v11, 0xffff0000, v100
	s_waitcnt lgkmcnt(1)
	v_lshlrev_b32_e32 v8, 16, v0
	v_and_b32_e32 v9, 0xffff0000, v0
	v_pk_mul_f32 v[8:9], v[10:11], v[8:9]
	v_lshlrev_b32_e32 v0, 16, v1
	v_and_b32_e32 v1, 0xffff0000, v1
	v_lshlrev_b32_e32 v10, 16, v101
	v_and_b32_e32 v11, 0xffff0000, v101
	v_pk_mul_f32 v[10:11], v[10:11], v[0:1]
	v_lshlrev_b32_e32 v0, 16, v2
	v_and_b32_e32 v1, 0xffff0000, v2
	v_lshlrev_b32_e32 v12, 16, v102
	v_and_b32_e32 v13, 0xffff0000, v102
	v_or_b32_e32 v16, s92, v104
	v_pk_mul_f32 v[12:13], v[12:13], v[0:1]
	v_lshlrev_b32_e32 v0, 16, v3
	v_and_b32_e32 v1, 0xffff0000, v3
	v_lshlrev_b32_e32 v2, 16, v103
	v_and_b32_e32 v3, 0xffff0000, v103
	v_ashrrev_i32_e32 v17, 31, v16
	v_pk_mul_f32 v[14:15], v[2:3], v[0:1]
	v_cvt_pk_bf16_f32 v0, v8, v9
	v_lshlrev_b64 v[8:9], 11, v[16:17]
	v_lshl_add_u64 v[8:9], s[46:47], 0, v[8:9]
	v_lshl_add_u64 v[8:9], v[8:9], 0, s[52:53]
	v_cvt_pk_bf16_f32 v1, v10, v11
	v_cvt_pk_bf16_f32 v2, v12, v13
	v_cvt_pk_bf16_f32 v3, v14, v15
	v_lshl_add_u64 v[8:9], v[8:9], 0, v[124:125]
	global_store_dwordx4 v[8:9], v[0:3], off offset:1024 sc1
	v_lshlrev_b32_e32 v8, 16, v98
	v_and_b32_e32 v9, 0xffff0000, v98
	s_waitcnt lgkmcnt(0)
	v_lshlrev_b32_e32 v0, 16, v4
	v_and_b32_e32 v1, 0xffff0000, v4
	v_lshlrev_b32_e32 v2, 16, v96
	v_and_b32_e32 v3, 0xffff0000, v96
	v_pk_mul_f32 v[0:1], v[2:3], v[0:1]
	v_lshlrev_b32_e32 v2, 16, v5
	v_and_b32_e32 v3, 0xffff0000, v5
	v_lshlrev_b32_e32 v4, 16, v97
	v_and_b32_e32 v5, 0xffff0000, v97
	v_pk_mul_f32 v[2:3], v[4:5], v[2:3]
	v_lshlrev_b32_e32 v4, 16, v6
	v_and_b32_e32 v5, 0xffff0000, v6
	v_pk_mul_f32 v[4:5], v[8:9], v[4:5]
	v_lshlrev_b32_e32 v6, 16, v7
	v_and_b32_e32 v7, 0xffff0000, v7
	v_lshlrev_b32_e32 v8, 16, v99
	v_and_b32_e32 v9, 0xffff0000, v99
	v_pk_mul_f32 v[6:7], v[8:9], v[6:7]
	v_or_b32_e32 v8, s92, v105
	v_ashrrev_i32_e32 v9, 31, v8
	v_cvt_pk_bf16_f32 v0, v0, v1
	v_cvt_pk_bf16_f32 v1, v2, v3
	v_cvt_pk_bf16_f32 v2, v4, v5
	v_lshlrev_b64 v[4:5], 11, v[8:9]
	v_lshl_add_u64 v[4:5], s[46:47], 0, v[4:5]
	v_lshl_add_u64 v[4:5], v[4:5], 0, s[52:53]
	v_cvt_pk_bf16_f32 v3, v6, v7
	v_lshl_add_u64 v[4:5], v[4:5], 0, v[124:125]
	global_store_dwordx4 v[4:5], v[0:3], off offset:1024 sc1
	s_waitcnt lgkmcnt(0)
	global_load_dwordx4 v[0:3], v[48:49], off
	global_load_dwordx4 v[4:7], v[48:49], off offset:16
	global_load_dwordx4 v[8:11], v[48:49], off offset:64
	global_load_dwordx4 v[12:15], v[48:49], off offset:80
	global_load_dwordx4 v[16:19], v[48:49], off offset:128
	global_load_dwordx4 v[20:23], v[48:49], off offset:144
	global_load_dwordx4 v[24:27], v[48:49], off offset:192
	global_load_dwordx4 v[28:31], v[48:49], off offset:208
	v_or_b32_e32 v32, s86, v132
	v_lshl_or_b32 v44, v32, 6, v224
	global_load_dwordx4 v[32:35], v44, s[48:49] offset:32
	global_load_dwordx4 v[36:39], v44, s[48:49] offset:48
	global_load_dwordx4 v[40:43], v44, s[48:49]
	s_nop 0
	global_load_dwordx4 v[44:47], v44, s[48:49] offset:16
	v_lshlrev_b32_e32 v166, 16, v80
	v_and_b32_e32 v167, 0xffff0000, v80
	v_lshlrev_b32_e32 v162, 16, v81
	v_and_b32_e32 v163, 0xffff0000, v81
	v_pk_mul_f32 v[80:81], v[166:167], v[166:167]
	v_pk_mul_f32 v[164:165], v[162:163], v[162:163]
	v_add_f32_e32 v53, v80, v81
	v_lshlrev_b32_e32 v160, 16, v82
	v_and_b32_e32 v161, 0xffff0000, v82
	v_add_f32_e32 v53, v164, v53
	v_lshlrev_b32_e32 v156, 16, v83
	v_and_b32_e32 v157, 0xffff0000, v83
	v_pk_mul_f32 v[82:83], v[160:161], v[160:161]
	v_add_f32_e32 v53, v165, v53
	v_add_f32_e32 v53, v82, v53
	v_pk_mul_f32 v[158:159], v[156:157], v[156:157]
	v_add_f32_e32 v53, v83, v53
	v_lshlrev_b32_e32 v154, 16, v84
	v_and_b32_e32 v155, 0xffff0000, v84
	v_add_f32_e32 v53, v158, v53
	v_lshlrev_b32_e32 v150, 16, v85
	v_and_b32_e32 v151, 0xffff0000, v85
	v_pk_mul_f32 v[84:85], v[154:155], v[154:155]
	v_add_f32_e32 v53, v159, v53
	v_add_f32_e32 v53, v84, v53
	v_pk_mul_f32 v[152:153], v[150:151], v[150:151]
	v_add_f32_e32 v53, v85, v53
	v_lshlrev_b32_e32 v132, 16, v86
	v_and_b32_e32 v133, 0xffff0000, v86
	v_add_f32_e32 v53, v152, v53
	v_lshlrev_b32_e32 v110, 16, v87
	v_and_b32_e32 v111, 0xffff0000, v87
	v_pk_mul_f32 v[86:87], v[132:133], v[132:133]
	v_add_f32_e32 v53, v153, v53
	v_add_f32_e32 v53, v86, v53
	v_pk_mul_f32 v[128:129], v[110:111], v[110:111]
	v_add_f32_e32 v53, v87, v53
	v_lshlrev_b32_e32 v108, 16, v88
	v_and_b32_e32 v109, 0xffff0000, v88
	v_add_f32_e32 v53, v128, v53
; __device__ __forceinline__ u32x4 pack8(const float (&f)[8]) { u32x4 w; w.x = pk_bf16(f[0], f[1]); w.y = pk_bf16(f[2], f[3]); w.z = pk_bf16(f[4], f[5]); w.w = pk_bf16(f[6], f[7]); return w; }
; template <bool SAMPLE> ...
;     ...
;     float ss = 0.f;
; #pragma unroll
;     for (int d0 = 0; d0 < 4; ++d0)
; #pragma unroll
;         for (int i = 0; i < 8; ++i) ss += q[d0][i] * q[d0][i];
;     ss += __shfl_xor(ss, 32);
;     const float rstd = rsqrtf(ss * (1.0f / 64.0f) + EPS);
; #pragma unroll
;     for (int d0 = 0; d0 < 4; ++d0) { const f32x4 g0 = *(const f32x4*)(qg + d0 * 16 + hi * 8), g1 = *(const f32x4*)(qg + d0 * 16 + hi * 8 + 4);
;         q[d0][0] *= rstd * g0.x; q[d0][1] *= rstd * g0.y; q[d0][2] *= rstd * g0.z; q[d0][3] *= rstd * g0.w; q[d0][4] *= rstd * g1.x; q[d0][5] *= rstd * g1.y; q[d0][6] *= rstd * g1.z; q[d0][7] *= rstd * g1.w; }
;     {
;         const float* tr = tab + (size_t)mypos * 16;
;         const f32x4 c0 = *(const f32x4*)(tr), c1 = *(const f32x4*)(tr + 4), s0 = *(const f32x4*)(tr + 8), s1 = *(const f32x4*)(tr + 12);
;         const float cs[8] = {c0.x, c0.y, c0.z, c0.w, c1.x, c1.y, c1.z, c1.w}, sn[8] = {s0.x, s0.y, s0.z, s0.w, s1.x, s1.y, s1.z, s1.w};
;         const float sg = (hi == 0) ? -1.0f : 1.0f;
; #pragma unroll
;         for (int i = 0; i < 8; ++i) { const float pr = __shfl_xor(q[0][i], 32); q[0][i] = q[0][i] * cs[i] + sg * pr * sn[i]; }
;     }
;     bf16x8 qr[4];
; #pragma unroll
;     for (int d0 = 0; d0 < 4; ++d0) {
; #pragma unroll
;         for (int i = 0; i < 8; ++i) q[d0][i] *= 0.125f * LOG2E;
;         qr[d0] = __builtin_bit_cast(bf16x8, pack8(q[d0])); }
;     f32x16 p[5];
;     const int rq = SAMPLE ? (r32 & 7) : r32;
;     const int lo = rq + 1 - 4 * hi, hi_ = rq - 4 * hi;
;     float mx = -1e30f;
; #pragma unroll
	v_lshlrev_b32_e32 v100, 16, v89
	v_and_b32_e32 v101, 0xffff0000, v89
	v_pk_mul_f32 v[88:89], v[108:109], v[108:109]
	v_add_f32_e32 v53, v129, v53
	v_add_f32_e32 v53, v88, v53
	v_pk_mul_f32 v[102:103], v[100:101], v[100:101]
	v_add_f32_e32 v53, v89, v53
	v_lshlrev_b32_e32 v98, 16, v90
	v_and_b32_e32 v99, 0xffff0000, v90
	v_add_f32_e32 v53, v102, v53
	v_lshlrev_b32_e32 v48, 16, v95
	v_and_b32_e32 v49, 0xffff0000, v95
	v_lshlrev_b32_e32 v54, 16, v94
	v_and_b32_e32 v55, 0xffff0000, v94
	v_lshlrev_b32_e32 v94, 16, v91
	v_and_b32_e32 v95, 0xffff0000, v91
	v_pk_mul_f32 v[90:91], v[98:99], v[98:99]
	v_add_f32_e32 v53, v103, v53
	v_add_f32_e32 v53, v90, v53
	v_pk_mul_f32 v[96:97], v[94:95], v[94:95]
	v_add_f32_e32 v53, v91, v53
	v_lshlrev_b32_e32 v62, 16, v92
	v_and_b32_e32 v63, 0xffff0000, v92
	v_add_f32_e32 v53, v96, v53
	v_lshlrev_b32_e32 v58, 16, v93
	v_and_b32_e32 v59, 0xffff0000, v93
	v_pk_mul_f32 v[92:93], v[62:63], v[62:63]
	v_add_f32_e32 v53, v97, v53
	v_add_f32_e32 v53, v92, v53
	v_pk_mul_f32 v[60:61], v[58:59], v[58:59]
	v_add_f32_e32 v53, v93, v53
	v_add_f32_e32 v53, v60, v53
	v_pk_mul_f32 v[56:57], v[54:55], v[54:55]
	v_add_f32_e32 v53, v61, v53
	v_add_f32_e32 v53, v56, v53
	v_pk_mul_f32 v[50:51], v[48:49], v[48:49]
	v_add_f32_e32 v53, v57, v53
	v_add_f32_e32 v50, v50, v53
	v_add_f32_e32 v50, v51, v50
	ds_bpermute_b32 v51, v127, v50
	v_mov_b32_e32 v102, 0xf149f2ca
	v_mov_b32_e32 v97, 0xf149f2ca
	v_mov_b32_e32 v92, 0xf149f2ca
	v_mov_b32_e32 v93, 0xf149f2ca
	s_waitcnt lgkmcnt(0)
	v_add_f32_e32 v50, v50, v51
	v_fmamk_f32 v50, v50, 0x3c800000, v209
	v_mul_f32_e32 v51, 0x4b800000, v50
	v_cmp_gt_f32_e32 vcc, s96, v50
	v_mov_b32_e32 v96, 0xf149f2ca
	v_mov_b32_e32 v103, 0xf149f2ca
	v_cndmask_b32_e32 v50, v50, v51, vcc
	v_rsq_f32_e32 v50, v50
	s_nop 0
	v_mul_f32_e32 v51, 0x45800000, v50
	v_cndmask_b32_e32 v50, v50, v51, vcc
	s_waitcnt vmcnt(11)
	v_pk_mul_f32 v[0:1], v[0:1], v[50:51] op_sel_hi:[1,0]
	v_pk_mul_f32 v[2:3], v[2:3], v[50:51] op_sel_hi:[1,0]
	v_pk_mul_f32 v[0:1], v[0:1], v[166:167]
	s_waitcnt vmcnt(10)
	v_pk_mul_f32 v[4:5], v[4:5], v[50:51] op_sel_hi:[1,0]
	v_pk_mul_f32 v[6:7], v[6:7], v[50:51] op_sel_hi:[1,0]
	s_waitcnt vmcnt(9)
	v_pk_mul_f32 v[8:9], v[8:9], v[50:51] op_sel_hi:[1,0]
	v_pk_mul_f32 v[10:11], v[10:11], v[50:51] op_sel_hi:[1,0]
	s_waitcnt vmcnt(8)
	v_pk_mul_f32 v[12:13], v[12:13], v[50:51] op_sel_hi:[1,0]
	v_pk_mul_f32 v[14:15], v[14:15], v[50:51] op_sel_hi:[1,0]
	s_waitcnt vmcnt(7)
	v_pk_mul_f32 v[16:17], v[16:17], v[50:51] op_sel_hi:[1,0]
	v_pk_mul_f32 v[18:19], v[18:19], v[50:51] op_sel_hi:[1,0]
	s_waitcnt vmcnt(6)
	v_pk_mul_f32 v[20:21], v[20:21], v[50:51] op_sel_hi:[1,0]
	v_pk_mul_f32 v[22:23], v[22:23], v[50:51] op_sel_hi:[1,0]
	s_waitcnt vmcnt(5)
	v_pk_mul_f32 v[24:25], v[24:25], v[50:51] op_sel_hi:[1,0]
	v_pk_mul_f32 v[26:27], v[26:27], v[50:51] op_sel_hi:[1,0]
	s_waitcnt vmcnt(4)
	v_pk_mul_f32 v[28:29], v[28:29], v[50:51] op_sel_hi:[1,0]
	ds_bpermute_b32 v51, v127, v1
	ds_bpermute_b32 v53, v127, v0
	v_pk_mul_f32 v[2:3], v[2:3], v[162:163]
	v_pk_mul_f32 v[4:5], v[4:5], v[160:161]
	v_pk_mul_f32 v[6:7], v[6:7], v[156:157]
	s_waitcnt lgkmcnt(1)
	v_pk_mul_f32 v[30:31], v[30:31], v[50:51] op_sel_hi:[1,0]
	ds_bpermute_b32 v50, v127, v3
	v_pk_mul_f32 v[30:31], v[30:31], v[48:49]
	v_cndmask_b32_e64 v49, v51, -v51, s[0:1]
	ds_bpermute_b32 v51, v127, v2
	s_waitcnt lgkmcnt(2)
	v_cndmask_b32_e64 v48, v53, -v53, s[0:1]
	s_waitcnt vmcnt(3)
	v_pk_mul_f32 v[32:33], v[32:33], v[48:49]
	v_pk_mul_f32 v[8:9], v[8:9], v[154:155]
	s_waitcnt vmcnt(1)
	v_pk_fma_f32 v[0:1], v[40:41], v[0:1], v[32:33]
	ds_bpermute_b32 v40, v127, v5
	s_waitcnt lgkmcnt(2)
	v_cndmask_b32_e64 v33, v50, -v50, s[0:1]
	s_waitcnt lgkmcnt(1)
	v_cndmask_b32_e64 v32, v51, -v51, s[0:1]
	v_pk_mul_f32 v[32:33], v[34:35], v[32:33]
	ds_bpermute_b32 v34, v127, v4
	v_pk_fma_f32 v[2:3], v[42:43], v[2:3], v[32:33]
	s_waitcnt lgkmcnt(1)
	v_cndmask_b32_e64 v33, v40, -v40, s[0:1]
	ds_bpermute_b32 v35, v127, v7
	ds_bpermute_b32 v40, v127, v6
	s_waitcnt lgkmcnt(2)
	v_cndmask_b32_e64 v32, v34, -v34, s[0:1]
	v_pk_mul_f32 v[32:33], v[36:37], v[32:33]
	v_pk_mul_f32 v[10:11], v[10:11], v[150:151]
	s_waitcnt vmcnt(0)
	v_pk_fma_f32 v[4:5], v[44:45], v[4:5], v[32:33]
	s_waitcnt lgkmcnt(1)
	v_cndmask_b32_e64 v33, v35, -v35, s[0:1]
	s_waitcnt lgkmcnt(0)
	v_cndmask_b32_e64 v32, v40, -v40, s[0:1]
	v_pk_mul_f32 v[32:33], v[38:39], v[32:33]
	v_pk_mul_f32 v[12:13], v[12:13], v[132:133]
	v_pk_fma_f32 v[6:7], v[46:47], v[6:7], v[32:33]
	v_pk_mul_f32 v[14:15], v[14:15], v[110:111]
	v_pk_mul_f32 v[0:1], v[0:1], s[90:91] op_sel_hi:[1,0]
	v_pk_mul_f32 v[2:3], v[2:3], s[90:91] op_sel_hi:[1,0]
	v_pk_mul_f32 v[4:5], v[4:5], s[90:91] op_sel_hi:[1,0]
	v_pk_mul_f32 v[6:7], v[6:7], s[90:91] op_sel_hi:[1,0]
	v_pk_mul_f32 v[16:17], v[16:17], v[108:109]
	v_pk_mul_f32 v[18:19], v[18:19], v[100:101]
	v_pk_mul_f32 v[20:21], v[20:21], v[98:99]
	v_pk_mul_f32 v[22:23], v[22:23], v[94:95]
	v_cvt_pk_bf16_f32 v48, v0, v1
	v_cvt_pk_bf16_f32 v49, v2, v3
	v_cvt_pk_bf16_f32 v50, v4, v5
	v_cvt_pk_bf16_f32 v51, v6, v7
	v_pk_mul_f32 v[0:1], v[8:9], s[90:91] op_sel_hi:[1,0]
	v_pk_mul_f32 v[2:3], v[10:11], s[90:91] op_sel_hi:[1,0]
	v_pk_mul_f32 v[4:5], v[12:13], s[90:91] op_sel_hi:[1,0]
	v_pk_mul_f32 v[6:7], v[14:15], s[90:91] op_sel_hi:[1,0]
	v_pk_mul_f32 v[24:25], v[24:25], v[62:63]
	v_pk_mul_f32 v[26:27], v[26:27], v[58:59]
	v_pk_mul_f32 v[28:29], v[28:29], v[54:55]
	v_cvt_pk_bf16_f32 v80, v0, v1
	v_cvt_pk_bf16_f32 v81, v2, v3
	v_cvt_pk_bf16_f32 v82, v4, v5
	v_cvt_pk_bf16_f32 v83, v6, v7
	v_pk_mul_f32 v[0:1], v[16:17], s[90:91] op_sel_hi:[1,0]
	v_pk_mul_f32 v[2:3], v[18:19], s[90:91] op_sel_hi:[1,0]
	v_pk_mul_f32 v[4:5], v[20:21], s[90:91] op_sel_hi:[1,0]
	v_pk_mul_f32 v[6:7], v[22:23], s[90:91] op_sel_hi:[1,0]
	v_cvt_pk_bf16_f32 v84, v0, v1
	v_cvt_pk_bf16_f32 v85, v2, v3
	v_cvt_pk_bf16_f32 v86, v4, v5
	v_cvt_pk_bf16_f32 v87, v6, v7
	v_pk_mul_f32 v[0:1], v[24:25], s[90:91] op_sel_hi:[1,0]
	v_pk_mul_f32 v[2:3], v[26:27], s[90:91] op_sel_hi:[1,0]
	v_pk_mul_f32 v[4:5], v[28:29], s[90:91] op_sel_hi:[1,0]
	v_pk_mul_f32 v[6:7], v[30:31], s[90:91] op_sel_hi:[1,0]
	v_add_u32_e32 v32, s82, v149
	v_cvt_pk_bf16_f32 v88, v0, v1
	v_cvt_pk_bf16_f32 v89, v2, v3
	v_cvt_pk_bf16_f32 v90, v4, v5
	v_cvt_pk_bf16_f32 v91, v6, v7
	v_mov_b32_e32 v0, 0xf149f2ca
	s_and_b64 vcc, exec, s[38:39]
	v_add_u32_e32 v125, v32, v52
	v_mov_b32_e32 v100, 0xf149f2ca
	v_mov_b32_e32 v99, 0xf149f2ca
	v_mov_b32_e32 v94, 0xf149f2ca
	v_mov_b32_e32 v95, 0xf149f2ca
	v_mov_b32_e32 v98, 0xf149f2ca
	v_mov_b32_e32 v101, 0xf149f2ca
	v_mov_b32_e32 v108, 0xf149f2ca
	v_mov_b32_e32 v109, 0xf149f2ca
	v_mov_b32_e32 v110, 0xf149f2ca
	v_mov_b32_e32 v111, 0xf149f2ca
	s_cbranch_vccnz .LBB0_489
; #define LAS __attribute__((address_space(3)))
; template <bool SAMPLE> ...
;     ...
;     for (int t = 0; t < 5; ++t) {
;         if (t >= tmin) {
; #pragma unroll
;             for (int i = 0; i < 16; ++i) p[t][i] = 0.f;
; #pragma unroll
;             for (int d0 = 0; d0 < 4; ++d0) { const bf16x8 kf = *(const LAS bf16x8*)(Kl + (32 * t + r32) * 144 + (16 * d0 + 8 * hi) * 2);
;                 p[t] = __builtin_amdgcn_mfma_f32_32x32x16_bf16(kf, qr[d0], p[t], 0, 0, 0); }
;             if (t == 0) {
; #pragma unroll
;                 for (int i = 0; i < 16; ++i) { const int kc = (i & 3) + 8 * (i >> 2); p[t][i] = (kc >= lo) ? p[t][i] : -1e30f; }
;             }
;             if (t == 4) {
; #pragma unroll
;                 for (int i = 0; i < 16; ++i) { const int kc = (i & 3) + 8 * (i >> 2); p[t][i] = (kc <= hi_) ? p[t][i] : -1e30f; }
;             }
	ds_read_b128 v[2:5], v125
	ds_read_b128 v[18:21], v125 offset:32
	v_cmp_gt_i32_e32 vcc, 1, v147
	s_waitcnt lgkmcnt(1)
	v_mfma_f32_32x32x16_bf16 v[2:17], v[2:5], v[48:51], 0
	s_waitcnt lgkmcnt(0)
	v_mfma_f32_32x32x16_bf16 v[2:17], v[18:21], v[80:83], v[2:17]
	ds_read_b128 v[18:21], v125 offset:64
	ds_read_b128 v[22:25], v125 offset:96
	s_waitcnt lgkmcnt(1)
	v_mfma_f32_32x32x16_bf16 v[2:17], v[18:21], v[84:87], v[2:17]
	s_waitcnt lgkmcnt(0)
	v_mfma_f32_32x32x16_bf16 v[2:17], v[22:25], v[88:91], v[2:17]
	s_nop 11
	v_cndmask_b32_e32 v102, v223, v2, vcc
	v_cmp_gt_i32_e32 vcc, 2, v147
	s_nop 1
	v_cndmask_b32_e32 v100, v223, v3, vcc
	v_cmp_gt_i32_e32 vcc, 3, v147
	s_nop 1
	v_cndmask_b32_e32 v99, v223, v4, vcc
	v_cmp_gt_i32_e32 vcc, 4, v147
	s_nop 1
	v_cndmask_b32_e32 v97, v223, v5, vcc
	v_cmp_gt_i32_e32 vcc, 9, v147
	s_nop 1
	v_cndmask_b32_e32 v92, v223, v6, vcc
	v_cmp_gt_i32_e32 vcc, 10, v147
	s_nop 1
	v_cndmask_b32_e32 v93, v223, v7, vcc
	v_cmp_gt_i32_e32 vcc, 11, v147
	s_nop 1
	v_cndmask_b32_e32 v94, v223, v8, vcc
	v_cmp_gt_i32_e32 vcc, 12, v147
	s_nop 1
	v_cndmask_b32_e32 v95, v223, v9, vcc
	v_cmp_gt_i32_e32 vcc, 17, v147
	s_nop 1
	v_cndmask_b32_e32 v96, v223, v10, vcc
	v_cmp_gt_i32_e32 vcc, 18, v147
	s_nop 1
	v_cndmask_b32_e32 v98, v223, v11, vcc
	v_cmp_gt_i32_e32 vcc, 19, v147
	s_nop 1
	v_cndmask_b32_e32 v101, v223, v12, vcc
	v_cmp_gt_i32_e32 vcc, 20, v147
	s_nop 1
	v_cndmask_b32_e32 v103, v223, v13, vcc
	v_cmp_gt_i32_e32 vcc, 25, v147
	s_nop 1
	v_cndmask_b32_e32 v108, v223, v14, vcc
	v_cmp_gt_i32_e32 vcc, 26, v147
	s_nop 1
	v_cndmask_b32_e32 v109, v223, v15, vcc
	v_cmp_gt_i32_e32 vcc, 27, v147
	s_nop 1
	v_cndmask_b32_e32 v110, v223, v16, vcc
	v_cmp_gt_i32_e32 vcc, 28, v147
	s_nop 1
	v_cndmask_b32_e32 v111, v223, v17, vcc

; __device__ __forceinline__ u32x4 pack8(const float (&f)[8]) { u32x4 w; w.x = pk_bf16(f[0], f[1]); w.y = pk_bf16(f[2], f[3]); w.z = pk_bf16(f[4], f[5]); w.w = pk_bf16(f[6], f[7]); return w; }
; __device__ __forceinline__ void conv_item(const Args& a, int l, int it, int lane, int wave) {
;     ...
; #pragma unroll
;     for (int i = 0; i < 8; ++i) {
;         float u0[8], gz[8], yv[8];
;         unpack8(uw[i], u0); unpack8(gw[i], gz);
; #pragma unroll
;         for (int k = 0; k < 8; ++k) { yv[k] = gz[k] * (w0[k] * u2[k] + w1[k] * u1[k] + w2[k] * u0[k]); u2[k] = u1[k]; u1[k] = u0[k]; }
;         *(u32x4*)(Y + (size_t)(t0 + i) * D + ch) = pack8(yv);
;     }
.LBB0_498:
	s_waitcnt vmcnt(1)
	v_pk_mul_f32 v[116:117], v[16:17], v[92:93]
	v_lshlrev_b32_e32 v112, 16, v84
	v_and_b32_e32 v113, 0xffff0000, v84
	v_pk_fma_f32 v[100:101], v[12:13], v[100:101], v[116:117]
	v_lshlrev_b32_e32 v114, 16, v80
	v_and_b32_e32 v115, 0xffff0000, v80
	v_pk_fma_f32 v[100:101], v[20:21], v[112:113], v[100:101]
	v_lshlrev_b32_e32 v84, 16, v85
	v_pk_mul_f32 v[100:101], v[100:101], v[114:115]
	v_pk_mul_f32 v[114:115], v[18:19], v[94:95]
	v_and_b32_e32 v85, 0xffff0000, v85
	v_pk_fma_f32 v[102:103], v[14:15], v[102:103], v[114:115]
	s_waitcnt vmcnt(0)
	v_pk_mul_f32 v[116:117], v[4:5], v[88:89]
	v_lshlrev_b32_e32 v80, 16, v81
	v_and_b32_e32 v81, 0xffff0000, v81
	v_pk_fma_f32 v[102:103], v[22:23], v[84:85], v[102:103]
	v_lshlrev_b32_e32 v114, 16, v86
	v_and_b32_e32 v115, 0xffff0000, v86
	v_pk_fma_f32 v[96:97], v[0:1], v[96:97], v[116:117]
	v_pk_mul_f32 v[102:103], v[102:103], v[80:81]
	v_lshlrev_b32_e32 v80, 16, v82
	v_and_b32_e32 v81, 0xffff0000, v82
	v_pk_fma_f32 v[96:97], v[8:9], v[114:115], v[96:97]
	v_lshlrev_b32_e32 v86, 16, v87
	v_pk_mul_f32 v[96:97], v[96:97], v[80:81]
	v_lshlrev_b32_e32 v80, 16, v83
	v_and_b32_e32 v81, 0xffff0000, v83
	v_pk_mul_f32 v[82:83], v[6:7], v[90:91]
	v_and_b32_e32 v87, 0xffff0000, v87
	v_pk_fma_f32 v[82:83], v[2:3], v[98:99], v[82:83]
	v_lshlrev_b32_e32 v172, 1, v109
	v_pk_fma_f32 v[82:83], v[10:11], v[86:87], v[82:83]
	v_lshl_add_u64 v[106:107], s[46:47], 0, v[172:173]
	v_pk_mul_f32 v[98:99], v[82:83], v[80:81]
	s_lshl_b64 s[20:21], s[0:1], 11
	v_cvt_pk_bf16_f32 v80, v100, v101
	v_cvt_pk_bf16_f32 v81, v102, v103
	v_cvt_pk_bf16_f32 v82, v96, v97
	v_cvt_pk_bf16_f32 v83, v98, v99
	v_lshl_add_u64 v[96:97], v[106:107], 0, s[20:21]
	v_pk_mul_f32 v[92:93], v[12:13], v[92:93]
	global_store_dwordx4 v[96:97], v[80:83], off sc1
	v_pk_fma_f32 v[92:93], v[16:17], v[112:113], v[92:93]
	v_pk_mul_f32 v[88:89], v[0:1], v[88:89]
	v_lshlrev_b32_e32 v80, 16, v76
	v_and_b32_e32 v81, 0xffff0000, v76
	v_lshlrev_b32_e32 v82, 16, v72
	v_and_b32_e32 v83, 0xffff0000, v72
	v_pk_fma_f32 v[92:93], v[20:21], v[80:81], v[92:93]
	v_lshlrev_b32_e32 v76, 16, v77
	v_pk_mul_f32 v[82:83], v[92:93], v[82:83]
	v_pk_mul_f32 v[92:93], v[14:15], v[94:95]
	v_and_b32_e32 v77, 0xffff0000, v77
	v_pk_fma_f32 v[92:93], v[18:19], v[84:85], v[92:93]
	v_lshlrev_b32_e32 v72, 16, v73
	v_and_b32_e32 v73, 0xffff0000, v73
	v_pk_fma_f32 v[92:93], v[22:23], v[76:77], v[92:93]
	v_lshlrev_b32_e32 v94, 16, v78
	v_and_b32_e32 v95, 0xffff0000, v78
	v_pk_fma_f32 v[88:89], v[4:5], v[114:115], v[88:89]
	v_pk_mul_f32 v[92:93], v[92:93], v[72:73]
	v_lshlrev_b32_e32 v72, 16, v74
	v_and_b32_e32 v73, 0xffff0000, v74
	v_pk_fma_f32 v[88:89], v[8:9], v[94:95], v[88:89]
	v_lshlrev_b32_e32 v78, 16, v79
	v_pk_mul_f32 v[88:89], v[88:89], v[72:73]
	v_lshlrev_b32_e32 v72, 16, v75
	v_and_b32_e32 v73, 0xffff0000, v75
	v_pk_mul_f32 v[74:75], v[2:3], v[90:91]
	v_and_b32_e32 v79, 0xffff0000, v79
	v_pk_fma_f32 v[74:75], v[6:7], v[86:87], v[74:75]
	s_lshl_b64 s[18:19], s[34:35], 11
	v_pk_fma_f32 v[74:75], v[10:11], v[78:79], v[74:75]
	s_lshl_b64 s[16:17], s[2:3], 11
	v_pk_mul_f32 v[90:91], v[74:75], v[72:73]
	v_cvt_pk_bf16_f32 v72, v82, v83
	v_cvt_pk_bf16_f32 v73, v92, v93
	v_cvt_pk_bf16_f32 v74, v88, v89
	v_cvt_pk_bf16_f32 v75, v90, v91
	v_lshl_add_u64 v[82:83], v[106:107], 0, s[18:19]
	global_store_dwordx4 v[82:83], v[72:75], off sc1
	v_pk_mul_f32 v[82:83], v[16:17], v[80:81]
	v_pk_mul_f32 v[88:89], v[4:5], v[94:95]
	v_lshlrev_b32_e32 v72, 16, v68
	v_and_b32_e32 v73, 0xffff0000, v68
	v_pk_fma_f32 v[82:83], v[12:13], v[112:113], v[82:83]
	v_lshlrev_b32_e32 v74, 16, v64
	v_and_b32_e32 v75, 0xffff0000, v64
	v_pk_fma_f32 v[82:83], v[20:21], v[72:73], v[82:83]
	v_lshlrev_b32_e32 v68, 16, v69
	v_pk_mul_f32 v[74:75], v[82:83], v[74:75]
	v_pk_mul_f32 v[82:83], v[18:19], v[76:77]
	v_and_b32_e32 v69, 0xffff0000, v69
	v_pk_fma_f32 v[82:83], v[14:15], v[84:85], v[82:83]
	v_lshlrev_b32_e32 v64, 16, v65
	v_and_b32_e32 v65, 0xffff0000, v65
	v_pk_fma_f32 v[82:83], v[22:23], v[68:69], v[82:83]
	v_lshlrev_b32_e32 v84, 16, v70
	v_and_b32_e32 v85, 0xffff0000, v70
	v_pk_fma_f32 v[88:89], v[0:1], v[114:115], v[88:89]
	v_pk_mul_f32 v[82:83], v[82:83], v[64:65]
	v_lshlrev_b32_e32 v64, 16, v66
	v_and_b32_e32 v65, 0xffff0000, v66
	v_pk_fma_f32 v[88:89], v[8:9], v[84:85], v[88:89]
	v_lshlrev_b32_e32 v70, 16, v71
	v_pk_mul_f32 v[88:89], v[88:89], v[64:65]
	v_lshlrev_b32_e32 v64, 16, v67
	v_and_b32_e32 v65, 0xffff0000, v67
	v_pk_mul_f32 v[66:67], v[6:7], v[78:79]
	v_and_b32_e32 v71, 0xffff0000, v71
	v_pk_fma_f32 v[66:67], v[2:3], v[86:87], v[66:67]
	s_lshl_b64 s[14:15], s[14:15], 11
	v_pk_fma_f32 v[66:67], v[10:11], v[70:71], v[66:67]
	s_lshl_b64 s[12:13], s[12:13], 11
	v_pk_mul_f32 v[86:87], v[66:67], v[64:65]
	v_cvt_pk_bf16_f32 v64, v74, v75
	v_cvt_pk_bf16_f32 v65, v82, v83
	v_cvt_pk_bf16_f32 v66, v88, v89
	v_cvt_pk_bf16_f32 v67, v86, v87
	v_lshl_add_u64 v[74:75], v[106:107], 0, s[16:17]
	global_store_dwordx4 v[74:75], v[64:67], off sc1
	v_pk_mul_f32 v[74:75], v[16:17], v[72:73]
	s_lshl_b64 s[10:11], s[10:11], 11
	v_lshlrev_b32_e32 v64, 16, v60
	v_and_b32_e32 v65, 0xffff0000, v60
	v_pk_fma_f32 v[74:75], v[12:13], v[80:81], v[74:75]
	v_lshlrev_b32_e32 v66, 16, v56
	v_and_b32_e32 v67, 0xffff0000, v56
	v_pk_fma_f32 v[74:75], v[20:21], v[64:65], v[74:75]
	v_lshlrev_b32_e32 v60, 16, v61
	v_pk_mul_f32 v[66:67], v[74:75], v[66:67]
	v_pk_mul_f32 v[74:75], v[18:19], v[68:69]
	v_and_b32_e32 v61, 0xffff0000, v61
	v_pk_fma_f32 v[74:75], v[14:15], v[76:77], v[74:75]
	v_pk_mul_f32 v[80:81], v[4:5], v[84:85]
	v_lshlrev_b32_e32 v56, 16, v57
	v_and_b32_e32 v57, 0xffff0000, v57
	v_pk_fma_f32 v[74:75], v[22:23], v[60:61], v[74:75]
; __device__ __forceinline__ u32x4 pack8(const float (&f)[8]) { u32x4 w; w.x = pk_bf16(f[0], f[1]); w.y = pk_bf16(f[2], f[3]); w.z = pk_bf16(f[4], f[5]); w.w = pk_bf16(f[6], f[7]); return w; }
; __device__ __forceinline__ void conv_item(const Args& a, int l, int it, int lane, int wave) {
;     ...
; #pragma unroll
;     for (int i = 0; i < 8; ++i) {
;         float u0[8], gz[8], yv[8];
;         unpack8(uw[i], u0); unpack8(gw[i], gz);
; #pragma unroll
;         for (int k = 0; k < 8; ++k) { yv[k] = gz[k] * (w0[k] * u2[k] + w1[k] * u1[k] + w2[k] * u0[k]); u2[k] = u1[k]; u1[k] = u0[k]; }
;         *(u32x4*)(Y + (size_t)(t0 + i) * D + ch) = pack8(yv);
;     }
	v_lshlrev_b32_e32 v76, 16, v62
	v_and_b32_e32 v77, 0xffff0000, v62
	v_pk_fma_f32 v[80:81], v[0:1], v[94:95], v[80:81]
	v_pk_mul_f32 v[74:75], v[74:75], v[56:57]
	v_lshlrev_b32_e32 v56, 16, v58
	v_and_b32_e32 v57, 0xffff0000, v58
	v_pk_fma_f32 v[80:81], v[8:9], v[76:77], v[80:81]
	v_lshlrev_b32_e32 v62, 16, v63
	v_pk_mul_f32 v[80:81], v[80:81], v[56:57]
	v_lshlrev_b32_e32 v56, 16, v59
	v_and_b32_e32 v57, 0xffff0000, v59
	v_pk_mul_f32 v[58:59], v[6:7], v[70:71]
	v_and_b32_e32 v63, 0xffff0000, v63
	v_pk_fma_f32 v[58:59], v[2:3], v[78:79], v[58:59]
	s_lshl_b64 s[8:9], s[8:9], 11
	v_pk_fma_f32 v[58:59], v[10:11], v[62:63], v[58:59]
	s_lshl_b64 s[4:5], s[4:5], 11
	v_pk_mul_f32 v[78:79], v[58:59], v[56:57]
	v_cvt_pk_bf16_f32 v56, v66, v67
	v_cvt_pk_bf16_f32 v57, v74, v75
	v_cvt_pk_bf16_f32 v58, v80, v81
	v_cvt_pk_bf16_f32 v59, v78, v79
	v_lshl_add_u64 v[66:67], v[106:107], 0, s[14:15]
	global_store_dwordx4 v[66:67], v[56:59], off sc1
	v_pk_mul_f32 v[66:67], v[16:17], v[64:65]
	s_and_b64 vcc, exec, s[6:7]
	v_lshlrev_b32_e32 v56, 16, v52
	v_and_b32_e32 v57, 0xffff0000, v52
	v_pk_fma_f32 v[66:67], v[12:13], v[72:73], v[66:67]
	v_lshlrev_b32_e32 v58, 16, v48
	v_and_b32_e32 v59, 0xffff0000, v48
	v_pk_fma_f32 v[66:67], v[20:21], v[56:57], v[66:67]
	v_lshlrev_b32_e32 v52, 16, v53
	v_pk_mul_f32 v[58:59], v[66:67], v[58:59]
	v_pk_mul_f32 v[66:67], v[18:19], v[60:61]
	v_and_b32_e32 v53, 0xffff0000, v53
	v_pk_fma_f32 v[66:67], v[14:15], v[68:69], v[66:67]
	v_pk_mul_f32 v[72:73], v[4:5], v[76:77]
	v_lshlrev_b32_e32 v48, 16, v49
	v_and_b32_e32 v49, 0xffff0000, v49
	v_pk_fma_f32 v[66:67], v[22:23], v[52:53], v[66:67]
	v_lshlrev_b32_e32 v68, 16, v54
	v_and_b32_e32 v69, 0xffff0000, v54
	v_pk_fma_f32 v[72:73], v[0:1], v[84:85], v[72:73]
	v_pk_mul_f32 v[66:67], v[66:67], v[48:49]
	v_lshlrev_b32_e32 v48, 16, v50
	v_and_b32_e32 v49, 0xffff0000, v50
	v_pk_fma_f32 v[72:73], v[8:9], v[68:69], v[72:73]
	v_lshlrev_b32_e32 v54, 16, v55
	v_pk_mul_f32 v[72:73], v[72:73], v[48:49]
	v_lshlrev_b32_e32 v48, 16, v51
	v_and_b32_e32 v49, 0xffff0000, v51
	v_pk_mul_f32 v[50:51], v[6:7], v[62:63]
	v_and_b32_e32 v55, 0xffff0000, v55
	v_pk_fma_f32 v[50:51], v[2:3], v[70:71], v[50:51]
	s_nop 0
	v_pk_fma_f32 v[50:51], v[10:11], v[54:55], v[50:51]
	s_nop 0
	v_pk_mul_f32 v[70:71], v[50:51], v[48:49]
	v_cvt_pk_bf16_f32 v48, v58, v59
	v_cvt_pk_bf16_f32 v49, v66, v67
	v_cvt_pk_bf16_f32 v50, v72, v73
	v_cvt_pk_bf16_f32 v51, v70, v71
	v_lshl_add_u64 v[58:59], v[106:107], 0, s[12:13]
	global_store_dwordx4 v[58:59], v[48:51], off sc1
	v_pk_mul_f32 v[58:59], v[16:17], v[56:57]
	s_nop 0
	v_lshlrev_b32_e32 v48, 16, v44
	v_and_b32_e32 v49, 0xffff0000, v44
	v_pk_fma_f32 v[58:59], v[12:13], v[64:65], v[58:59]
	v_lshlrev_b32_e32 v50, 16, v40
	v_and_b32_e32 v51, 0xffff0000, v40
	v_pk_fma_f32 v[58:59], v[20:21], v[48:49], v[58:59]
	v_lshlrev_b32_e32 v44, 16, v45
	v_pk_mul_f32 v[50:51], v[58:59], v[50:51]
	v_pk_mul_f32 v[58:59], v[18:19], v[52:53]
	v_and_b32_e32 v45, 0xffff0000, v45
	v_pk_fma_f32 v[58:59], v[14:15], v[60:61], v[58:59]
	v_pk_mul_f32 v[64:65], v[4:5], v[68:69]
	v_lshlrev_b32_e32 v40, 16, v41
	v_and_b32_e32 v41, 0xffff0000, v41
	v_pk_fma_f32 v[58:59], v[22:23], v[44:45], v[58:59]
	v_lshlrev_b32_e32 v60, 16, v46
	v_and_b32_e32 v61, 0xffff0000, v46
	v_pk_fma_f32 v[64:65], v[0:1], v[76:77], v[64:65]
	v_pk_mul_f32 v[58:59], v[58:59], v[40:41]
	v_lshlrev_b32_e32 v40, 16, v42
	v_and_b32_e32 v41, 0xffff0000, v42
	v_pk_fma_f32 v[64:65], v[8:9], v[60:61], v[64:65]
	v_lshlrev_b32_e32 v46, 16, v47
	v_pk_mul_f32 v[64:65], v[64:65], v[40:41]
	v_lshlrev_b32_e32 v40, 16, v43
	v_and_b32_e32 v41, 0xffff0000, v43
	v_pk_mul_f32 v[42:43], v[6:7], v[54:55]
	v_and_b32_e32 v47, 0xffff0000, v47
	v_pk_fma_f32 v[42:43], v[2:3], v[62:63], v[42:43]
	s_nop 0
; __device__ __forceinline__ u32x4 pack8(const float (&f)[8]) { u32x4 w; w.x = pk_bf16(f[0], f[1]); w.y = pk_bf16(f[2], f[3]); w.z = pk_bf16(f[4], f[5]); w.w = pk_bf16(f[6], f[7]); return w; }
; __device__ __forceinline__ void conv_item(const Args& a, int l, int it, int lane, int wave) {
;     ...
; #pragma unroll
;     for (int i = 0; i < 8; ++i) {
;         float u0[8], gz[8], yv[8];
;         unpack8(uw[i], u0); unpack8(gw[i], gz);
; #pragma unroll
;         for (int k = 0; k < 8; ++k) { yv[k] = gz[k] * (w0[k] * u2[k] + w1[k] * u1[k] + w2[k] * u0[k]); u2[k] = u1[k]; u1[k] = u0[k]; }
;         *(u32x4*)(Y + (size_t)(t0 + i) * D + ch) = pack8(yv);
;     }
;     float* oc = nullptr;
;     if (t0 < MP) { if ((t0 & (LP - 1)) == LP - 8) oc = a.out + O_CP + ((size_t)(l * NPB + (t0 >> 12)) * 2) * 512 + ch; }
;     else oc = a.out + O_CS + ((size_t)(l * NSB + ((t0 - MP) >> 3)) * 2) * 512 + ch;
;     if (oc) { *(f32x4*)oc = (f32x4){u2[0], u2[1], u2[2], u2[3]}; *(f32x4*)(oc + 4) = (f32x4){u2[4], u2[5], u2[6], u2[7]};
;               *(f32x4*)(oc + 512) = (f32x4){u1[0], u1[1], u1[2], u1[3]}; *(f32x4*)(oc + 516) = (f32x4){u1[4], u1[5], u1[6], u1[7]}; }
	v_pk_fma_f32 v[42:43], v[10:11], v[46:47], v[42:43]
	s_nop 0
	v_pk_mul_f32 v[62:63], v[42:43], v[40:41]
	v_cvt_pk_bf16_f32 v40, v50, v51
	v_cvt_pk_bf16_f32 v41, v58, v59
	v_cvt_pk_bf16_f32 v42, v64, v65
	v_cvt_pk_bf16_f32 v43, v62, v63
	v_lshl_add_u64 v[50:51], v[106:107], 0, s[10:11]
	global_store_dwordx4 v[50:51], v[40:43], off sc1
	v_pk_mul_f32 v[50:51], v[16:17], v[48:49]
	s_nop 0
	v_lshlrev_b32_e32 v40, 16, v36
	v_and_b32_e32 v41, 0xffff0000, v36
	v_pk_fma_f32 v[50:51], v[12:13], v[56:57], v[50:51]
	v_lshlrev_b32_e32 v42, 16, v32
	v_and_b32_e32 v43, 0xffff0000, v32
	v_pk_fma_f32 v[50:51], v[20:21], v[40:41], v[50:51]
	v_lshlrev_b32_e32 v32, 16, v33
	v_pk_mul_f32 v[50:51], v[50:51], v[42:43]
	v_lshlrev_b32_e32 v42, 16, v37
	v_and_b32_e32 v43, 0xffff0000, v37
	v_pk_mul_f32 v[36:37], v[18:19], v[44:45]
	v_and_b32_e32 v33, 0xffff0000, v33
	v_pk_fma_f32 v[36:37], v[14:15], v[52:53], v[36:37]
	v_pk_mul_f32 v[56:57], v[4:5], v[60:61]
	v_pk_fma_f32 v[36:37], v[22:23], v[42:43], v[36:37]
	v_pk_fma_f32 v[56:57], v[0:1], v[68:69], v[56:57]
	v_pk_mul_f32 v[52:53], v[36:37], v[32:33]
	v_lshlrev_b32_e32 v36, 16, v38
	v_and_b32_e32 v37, 0xffff0000, v38
	v_lshlrev_b32_e32 v32, 16, v34
	v_and_b32_e32 v33, 0xffff0000, v34
	v_pk_fma_f32 v[56:57], v[8:9], v[36:37], v[56:57]
	v_lshlrev_b32_e32 v38, 16, v39
	v_pk_mul_f32 v[56:57], v[56:57], v[32:33]
	v_lshlrev_b32_e32 v32, 16, v35
	v_and_b32_e32 v33, 0xffff0000, v35
	v_pk_mul_f32 v[34:35], v[6:7], v[46:47]
	v_and_b32_e32 v39, 0xffff0000, v39
	v_pk_fma_f32 v[34:35], v[2:3], v[54:55], v[34:35]
	v_pk_mul_f32 v[16:17], v[16:17], v[40:41]
	v_pk_fma_f32 v[34:35], v[10:11], v[38:39], v[34:35]
	v_pk_fma_f32 v[12:13], v[12:13], v[48:49], v[16:17]
	v_pk_mul_f32 v[54:55], v[34:35], v[32:33]
	v_cvt_pk_bf16_f32 v32, v50, v51
	v_cvt_pk_bf16_f32 v33, v52, v53
	v_cvt_pk_bf16_f32 v34, v56, v57
	v_cvt_pk_bf16_f32 v35, v54, v55
	v_lshl_add_u64 v[50:51], v[106:107], 0, s[8:9]
	global_store_dwordx4 v[50:51], v[32:35], off sc1
	v_pk_mul_f32 v[18:19], v[18:19], v[42:43]
	v_pk_mul_f32 v[4:5], v[4:5], v[36:37]
	v_lshlrev_b32_e32 v32, 16, v28
	v_and_b32_e32 v33, 0xffff0000, v28
	v_lshlrev_b32_e32 v34, 16, v24
	v_and_b32_e32 v35, 0xffff0000, v24
	v_pk_fma_f32 v[12:13], v[20:21], v[32:33], v[12:13]
	v_pk_fma_f32 v[14:15], v[14:15], v[44:45], v[18:19]
	v_pk_mul_f32 v[16:17], v[12:13], v[34:35]
	v_lshlrev_b32_e32 v34, 16, v29
	v_and_b32_e32 v35, 0xffff0000, v29
	v_lshlrev_b32_e32 v12, 16, v25
	v_and_b32_e32 v13, 0xffff0000, v25
	v_pk_fma_f32 v[14:15], v[22:23], v[34:35], v[14:15]
	v_pk_fma_f32 v[0:1], v[0:1], v[60:61], v[4:5]
	v_pk_mul_f32 v[18:19], v[14:15], v[12:13]
	v_lshlrev_b32_e32 v12, 16, v30
	v_and_b32_e32 v13, 0xffff0000, v30
	v_lshlrev_b32_e32 v14, 16, v26
	v_and_b32_e32 v15, 0xffff0000, v26
	v_pk_fma_f32 v[0:1], v[8:9], v[12:13], v[0:1]
	v_pk_mul_f32 v[6:7], v[6:7], v[38:39]
	v_pk_mul_f32 v[4:5], v[0:1], v[14:15]
	v_lshlrev_b32_e32 v14, 16, v31
	v_and_b32_e32 v15, 0xffff0000, v31
	v_pk_fma_f32 v[2:3], v[2:3], v[46:47], v[6:7]
	v_lshlrev_b32_e32 v0, 16, v27
	v_and_b32_e32 v1, 0xffff0000, v27
	v_pk_fma_f32 v[2:3], v[10:11], v[14:15], v[2:3]
	s_nop 0
	v_pk_mul_f32 v[6:7], v[2:3], v[0:1]
	v_cvt_pk_bf16_f32 v0, v16, v17
	v_cvt_pk_bf16_f32 v1, v18, v19
	v_cvt_pk_bf16_f32 v2, v4, v5
	v_cvt_pk_bf16_f32 v3, v6, v7
	v_lshl_add_u64 v[4:5], v[106:107], 0, s[4:5]
	s_mov_b64 s[4:5], -1
	global_store_dwordx4 v[4:5], v[0:3], off sc1
	s_cbranch_vccz .LBB0_515
	s_add_i32 s1, s0, 0xffffc000
	s_lshr_b32 s1, s1, 2
	v_readlane_b32 s2, v255, 18
	s_add_i32 s86, s1, s2
	s_lshl_b64 s[4:5], s[86:87], 11
	v_readlane_b32 s1, v254, 14
	s_add_u32 s4, s1, s4
	v_readlane_b32 s1, v254, 15
	s_addc_u32 s5, s1, s5
	v_mov_b32_e32 v105, v173
	v_lshl_add_u64 v[0:1], s[4:5], 0, v[104:105]
	s_cbranch_execz .LBB0_516

; __device__ __forceinline__ void conv_item(const Args& a, int l, int it, int lane, int wave) {
;     ...
;     float* oc = nullptr;
;     if (t0 < MP) { if ((t0 & (LP - 1)) == LP - 8) oc = a.out + O_CP + ((size_t)(l * NPB + (t0 >> 12)) * 2) * 512 + ch; }
;     else oc = a.out + O_CS + ((size_t)(l * NSB + ((t0 - MP) >> 3)) * 2) * 512 + ch;
;     if (oc) { *(f32x4*)oc = (f32x4){u2[0], u2[1], u2[2], u2[3]}; *(f32x4*)(oc + 4) = (f32x4){u2[4], u2[5], u2[6], u2[7]};
;               *(f32x4*)(oc + 512) = (f32x4){u1[0], u1[1], u1[2], u1[3]}; *(f32x4*)(oc + 516) = (f32x4){u1[4], u1[5], u1[6], u1[7]}; }
.LBB0_501:
	global_store_dwordx4 v[0:1], v[40:43], off sc1
	global_store_dwordx4 v[0:1], v[36:39], off offset:16 sc1
	global_store_dwordx4 v[0:1], v[32:35], off offset:2048 sc1
	global_store_dwordx4 v[0:1], v[12:15], off offset:2064 sc1

; #define LAS __attribute__((address_space(3)))
; __device__ __forceinline__ u32x4 pack8(const float (&f)[8]) { u32x4 w; w.x = pk_bf16(f[0], f[1]); w.y = pk_bf16(f[2], f[3]); w.z = pk_bf16(f[4], f[5]); w.w = pk_bf16(f[6], f[7]); return w; }
; __device__ __forceinline__ void attn_sample_item(const Args& a, int l, int n, LAS unsigned char* lds, int tid, int lane, int wave) {
;     ...
;     if (wave < 2) {
;         const int t = tid >> 4; const size_t row = (size_t)MP + n * LS + t;
;         const u32x4 kw = *(const u32x4*)(proj + row * PO2 + C_K + kvh * 64 + sub * 8);
;         const u32x4 vw = *(const u32x4*)(proj + row * PO2 + C_V + kvh * 64 + sub * 8);
;         float kf[8]; unpack8(kw, kf);
;         normrope8(kf, sub, kg, tab + (size_t)(LP + t) * 16);
;         *(LAS u32x4*)(lds + kvh * KH + (128 + t) * 144 + sub * 16) = pack8(kf);
;         *(LAS u32x4*)(lds + VOFF + kvh * 2 * VH + (sub >> 2) * VH + (128 + t) * 64 + (sub & 3) * 16) = vw;
;         float vf[8]; unpack8(vw, vf);
;         float* pk = oks + (120 + t) * 128 + c16 * 8; float* pv = ovs + (120 + t) * 128 + c16 * 8;
;         *(f32x4*)pk = (f32x4){kf[0], kf[1], kf[2], kf[3]}; *(f32x4*)(pk + 4) = (f32x4){kf[4], kf[5], kf[6], kf[7]};
;         *(f32x4*)pv = (f32x4){vf[0], vf[1], vf[2], vf[3]}; *(f32x4*)(pv + 4) = (f32x4){vf[4], vf[5], vf[6], vf[7]};
;     }
;     for (int e = tid; e < 2 * 216 + 4 * 96; e += 512) {
.LBB0_520:
	s_or_b64 exec, exec, s[0:1]
	s_waitcnt lgkmcnt(7)
	v_cvt_pk_bf16_f32 v28, v24, v25
	s_waitcnt lgkmcnt(5)
	v_cvt_pk_bf16_f32 v29, v26, v27
	s_waitcnt lgkmcnt(3)
	v_cvt_pk_bf16_f32 v30, v20, v21
	v_cvt_pk_bf16_f32 v31, v22, v23
	v_add3_u32 v32, v32, v110, v98
	s_waitcnt lgkmcnt(2)
	v_lshlrev_b32_e32 v33, 6, v100
	ds_write_b128 v32, v[28:31] offset:4608
	v_lshl_add_u32 v32, v100, 7, v226
	v_add3_u32 v28, v33, v112, v111
	v_ashrrev_i32_e32 v33, 31, v32
	v_lshlrev_b32_e32 v36, 3, v97
	v_lshlrev_b64 v[32:33], 2, v[32:33]
	s_waitcnt lgkmcnt(1)
	v_lshl_add_u64 v[34:35], s[6:7], 0, v[32:33]
	v_lshlrev_b32_e32 v172, 2, v36
	v_lshl_add_u64 v[34:35], v[34:35], 0, v[172:173]
	v_lshl_add_u64 v[32:33], s[4:5], 0, v[32:33]
	s_waitcnt vmcnt(0)
	ds_write_b128 v28, v[16:19] offset:54272
	v_lshlrev_b32_e32 v28, 16, v16
	v_and_b32_e32 v29, 0xffff0000, v16
	v_lshlrev_b32_e32 v30, 16, v17
	v_and_b32_e32 v31, 0xffff0000, v17
	v_lshlrev_b32_e32 v16, 16, v18
	v_and_b32_e32 v17, 0xffff0000, v18
	v_lshlrev_b32_e32 v18, 16, v19
	v_and_b32_e32 v19, 0xffff0000, v19
	v_lshl_add_u64 v[32:33], v[32:33], 0, v[172:173]
	global_store_dwordx4 v[34:35], v[24:27], off sc1
	global_store_dwordx4 v[34:35], v[20:23], off offset:16 sc1
	global_store_dwordx4 v[32:33], v[28:31], off sc1
	global_store_dwordx4 v[32:33], v[16:19], off offset:16 sc1
	s_movk_i32 s0, 0x330
	v_cmp_gt_i32_e32 vcc, s0, v130
	s_and_saveexec_b64 s[0:1], vcc
	s_cbranch_execz .LBB0_527

; #define LAS __attribute__((address_space(3)))
; __device__ __forceinline__ int crow(int r, int hi) { return (r & 3) + 8 * (r >> 2) + 4 * hi; }
; __device__ __forceinline__ s16x4 vtr(const LAS unsigned char* p) { return __builtin_bit_cast(s16x4, __builtin_amdgcn_ds_read_tr16_b64_v4i16((LAS v4i16_t*)p)); }
; template <bool SAMPLE> ...
;     ...
;     u32x4 pw[5][2];
; #pragma unroll
;     for (int t = 0; t < 5; ++t) {
; #pragma unroll
;         for (int i = 0; i < 16; ++i) { p[t][i] = __builtin_amdgcn_exp2f(p[t][i] - mx); lsum += p[t][i]; }
; #pragma unroll
;         for (int s = 0; s < 2; ++s) { pw[t][s].x = pk_bf16(p[t][8 * s + 0], p[t][8 * s + 1]); pw[t][s].y = pk_bf16(p[t][8 * s + 2], p[t][8 * s + 3]); pw[t][s].z = pk_bf16(p[t][8 * s + 4], p[t][8 * s + 5]); pw[t][s].w = pk_bf16(p[t][8 * s + 6], p[t][8 * s + 7]); }
;     }
;     lsum += __shfl_xor(lsum, 32);
;     const float denom = lsum + __builtin_amdgcn_exp2f(sk - mx);
;     if (hi == 0) wsf[r32] = 1.0f / denom;
;     __builtin_amdgcn_sched_barrier(0);
;     f32x16 o[2];
; #pragma unroll
;     for (int d0 = 0; d0 < 2; ++d0)
; #pragma unroll
;         for (int i = 0; i < 16; ++i) o[d0][i] = 0.f;
;     const int i16 = lane & 15;
;     const LAS unsigned char* vb = Vl + (4 * hi + (i16 >> 2)) * 64 + ((lane >> 4) & 1) * 32 + (i16 & 3) * 8;
; #pragma unroll
;     for (int t = 0; t < 5; ++t)
; #pragma unroll
;         for (int s = 0; s < 2; ++s) {
;             const bf16x8 pa = __builtin_bit_cast(bf16x8, pw[t][s]);
; #pragma unroll
;             for (int d0 = 0; d0 < 2; ++d0) {
;                 const s16x4 vlo = vtr(vb + d0 * vhalf + (32 * t + 16 * s) * 64), vhi = vtr(vb + d0 * vhalf + (32 * t + 16 * s + 8) * 64);
;                 const bf16x8 vf = (bf16x8){vlo[0], vlo[1], vlo[2], vlo[3], vhi[0], vhi[1], vhi[2], vhi[3]};
;                 o[d0] = __builtin_amdgcn_mfma_f32_32x32x16_bf16(pa, vf, o[d0], 0, 0, 0);
;             }
;         }
;     __builtin_amdgcn_sched_barrier(0);
;     asm volatile("s_waitcnt lgkmcnt(0)" ::: "memory");
; #pragma unroll
;     for (int i = 0; i < 16; ++i) {
;         const int qq = crow(i, hi);
;         const float rl = wsf[qq];
; #pragma unroll
;         for (int d0 = 0; d0 < 2; ++d0) ost[qq * 64 + d0 * 32 + r32] = (bf16_t)(pk_bf16(o[d0][i] * rl, 0.f) & 0xffffu);
.LBB0_530:
	s_or_b64 exec, exec, s[0:1]
	s_lshl_b32 s0, s36, 3
	v_cvt_pk_bf16_f32 v32, v32, v32
	s_addk_i32 s0, 0x4000
	v_mov_b32_e32 v33, v32
	s_waitcnt lgkmcnt(0)
	v_mov_b32_e32 v34, v32
	v_mov_b32_e32 v35, v32
	v_cvt_pk_bf16_f32 v36, v36, v37
	v_cvt_pk_bf16_f32 v37, v38, v39
	v_mov_b32_e32 v38, v32
	v_mov_b32_e32 v39, v32
	v_cvt_pk_bf16_f32 v40, v8, v9
	v_cvt_pk_bf16_f32 v41, v10, v11
	v_cvt_pk_bf16_f32 v42, v12, v13
	v_cvt_pk_bf16_f32 v43, v14, v15
	v_cvt_pk_bf16_f32 v44, v0, v1
	v_cvt_pk_bf16_f32 v45, v2, v3
	v_cvt_pk_bf16_f32 v46, v4, v5
	v_cvt_pk_bf16_f32 v47, v6, v7
	v_cvt_pk_bf16_f32 v110, v24, v25
	v_cvt_pk_bf16_f32 v111, v26, v27
	v_cvt_pk_bf16_f32 v112, v28, v29
	v_cvt_pk_bf16_f32 v113, v30, v31
	v_cvt_pk_bf16_f32 v114, v16, v17
	v_cvt_pk_bf16_f32 v115, v18, v19
	v_cvt_pk_bf16_f32 v116, v20, v21
	v_cvt_pk_bf16_f32 v117, v22, v23
	v_cvt_pk_bf16_f32 v72, v72, v73
	v_cvt_pk_bf16_f32 v73, v74, v77
	v_cvt_pk_bf16_f32 v74, v78, v79
	v_cvt_pk_bf16_f32 v75, v101, v102
	v_cvt_pk_bf16_f32 v64, v64, v65
	v_cvt_pk_bf16_f32 v65, v66, v67
	v_cvt_pk_bf16_f32 v66, v68, v69
	v_cvt_pk_bf16_f32 v67, v70, v71
	v_cvt_pk_bf16_f32 v56, v56, v57
	v_cvt_pk_bf16_f32 v57, v58, v59
	v_cvt_pk_bf16_f32 v58, v60, v61
	v_cvt_pk_bf16_f32 v59, v62, v63
	v_cvt_pk_bf16_f32 v16, v48, v49
	v_cvt_pk_bf16_f32 v17, v50, v51
	v_cvt_pk_bf16_f32 v18, v52, v53
	v_cvt_pk_bf16_f32 v19, v54, v55
	v_lshrrev_b32_e32 v0, 2, v130
	v_and_or_b32 v0, v0, 3, v100
	v_readlane_b32 s1, v255, 29
	v_lshlrev_b32_e32 v1, 1, v108
	v_and_b32_e32 v1, 32, v1
	v_lshl_add_u32 v0, v0, 6, s1
	v_and_b32_e32 v2, 24, v109
	v_add3_u32 v52, v0, v1, v2
	ds_read_b64_tr_b16 v[0:1], v52 offset:46080
	ds_read_b64_tr_b16 v[2:3], v52 offset:46592
	s_waitcnt lgkmcnt(0)
	v_mfma_f32_32x32x16_bf16 v[0:15], v[16:19], v[0:3], 0
	ds_read_b64_tr_b16 v[20:21], v52 offset:56320
	ds_read_b64_tr_b16 v[22:23], v52 offset:56832
	ds_read_b64_tr_b16 v[48:49], v52 offset:47104
	ds_read_b64_tr_b16 v[50:51], v52 offset:47616
	s_waitcnt lgkmcnt(2)
	v_mfma_f32_32x32x16_bf16 v[16:31], v[16:19], v[20:23], 0
	s_waitcnt lgkmcnt(0)
	v_mfma_f32_32x32x16_bf16 v[0:15], v[56:59], v[48:51], v[0:15]
	ds_read_b64_tr_b16 v[48:49], v52 offset:57344
	ds_read_b64_tr_b16 v[50:51], v52 offset:57856
	s_waitcnt lgkmcnt(0)
	v_mfma_f32_32x32x16_bf16 v[16:31], v[56:59], v[48:51], v[16:31]
	ds_read_b64_tr_b16 v[48:49], v52 offset:48128
	ds_read_b64_tr_b16 v[50:51], v52 offset:48640
	s_waitcnt lgkmcnt(0)
	v_mfma_f32_32x32x16_bf16 v[0:15], v[64:67], v[48:51], v[0:15]
	ds_read_b64_tr_b16 v[48:49], v52 offset:58368
	ds_read_b64_tr_b16 v[50:51], v52 offset:58880
	s_waitcnt lgkmcnt(0)
	v_mfma_f32_32x32x16_bf16 v[16:31], v[64:67], v[48:51], v[16:31]
	ds_read_b64_tr_b16 v[48:49], v52 offset:49152
	ds_read_b64_tr_b16 v[50:51], v52 offset:49664
	s_waitcnt lgkmcnt(0)
	v_mfma_f32_32x32x16_bf16 v[0:15], v[72:75], v[48:51], v[0:15]
	ds_read_b64_tr_b16 v[48:49], v52 offset:59392
	ds_read_b64_tr_b16 v[50:51], v52 offset:59904
	s_waitcnt lgkmcnt(0)
	v_mfma_f32_32x32x16_bf16 v[16:31], v[72:75], v[48:51], v[16:31]
	ds_read_b64_tr_b16 v[48:49], v52 offset:50176
	ds_read_b64_tr_b16 v[50:51], v52 offset:50688
	s_waitcnt lgkmcnt(0)
	v_mfma_f32_32x32x16_bf16 v[0:15], v[114:117], v[48:51], v[0:15]
	ds_read_b64_tr_b16 v[48:49], v52 offset:60416
	ds_read_b64_tr_b16 v[50:51], v52 offset:60928
	s_waitcnt lgkmcnt(0)
	v_mfma_f32_32x32x16_bf16 v[16:31], v[114:117], v[48:51], v[16:31]
	ds_read_b64_tr_b16 v[48:49], v52 offset:51200
	ds_read_b64_tr_b16 v[50:51], v52 offset:51712
	s_waitcnt lgkmcnt(0)
	v_mfma_f32_32x32x16_bf16 v[0:15], v[110:113], v[48:51], v[0:15]
	ds_read_b64_tr_b16 v[48:49], v52 offset:61440
	ds_read_b64_tr_b16 v[50:51], v52 offset:61952
	s_waitcnt lgkmcnt(0)
	v_mfma_f32_32x32x16_bf16 v[16:31], v[110:113], v[48:51], v[16:31]
	ds_read_b64_tr_b16 v[48:49], v52 offset:52224
	ds_read_b64_tr_b16 v[50:51], v52 offset:52736
	s_waitcnt lgkmcnt(0)
	v_mfma_f32_32x32x16_bf16 v[0:15], v[44:47], v[48:51], v[0:15]
	ds_read_b64_tr_b16 v[48:49], v52 offset:62464
	ds_read_b64_tr_b16 v[50:51], v52 offset:62976
	s_waitcnt lgkmcnt(0)
	v_mfma_f32_32x32x16_bf16 v[16:31], v[44:47], v[48:51], v[16:31]
	ds_read_b64_tr_b16 v[44:45], v52 offset:53248
	ds_read_b64_tr_b16 v[46:47], v52 offset:53760
	s_waitcnt lgkmcnt(0)
	v_mfma_f32_32x32x16_bf16 v[0:15], v[40:43], v[44:47], v[0:15]
	ds_read_b64_tr_b16 v[44:45], v52 offset:63488
	ds_read_b64_tr_b16 v[46:47], v52 offset:64000
	s_waitcnt lgkmcnt(0)
	v_mfma_f32_32x32x16_bf16 v[16:31], v[40:43], v[44:47], v[16:31]
	ds_read_b64_tr_b16 v[40:41], v52 offset:54272
	ds_read_b64_tr_b16 v[42:43], v52 offset:54784
	s_waitcnt lgkmcnt(0)
	v_mfma_f32_32x32x16_bf16 v[0:15], v[36:39], v[40:43], v[0:15]
	ds_read_b64_tr_b16 v[40:41], v52 offset:64512
	ds_read_b64_tr_b16 v[42:43], v52 offset:65024
	s_waitcnt lgkmcnt(0)
	v_mfma_f32_32x32x16_bf16 v[16:31], v[36:39], v[40:43], v[16:31]
	ds_read_b64_tr_b16 v[36:37], v52 offset:55296
	ds_read_b64_tr_b16 v[38:39], v52 offset:55808
	s_waitcnt lgkmcnt(0)
	v_mfma_f32_32x32x16_bf16 v[0:15], v[32:35], v[36:39], v[0:15]
	v_add_u32_e32 v38, 0xb400, v52
	ds_read_b64_tr_b16 v[36:37], v38 offset:19456
	ds_read_b64_tr_b16 v[38:39], v38 offset:19968
	s_waitcnt lgkmcnt(0)
	v_mfma_f32_32x32x16_bf16 v[16:31], v[32:35], v[36:39], v[16:31]
	v_readlane_b32 s1, v255, 19
	s_waitcnt lgkmcnt(0)
	s_nop 1
	v_lshl_add_u32 v40, v100, 2, s1
	ds_read_b128 v[32:35], v40
	ds_read_b128 v[36:39], v40 offset:32
	v_readlane_b32 s1, v255, 20
	s_waitcnt lgkmcnt(1)
; #define LAS __attribute__((address_space(3)))
; __device__ __forceinline__ u32x4 pack8(const float (&f)[8]) { u32x4 w; w.x = pk_bf16(f[0], f[1]); w.y = pk_bf16(f[2], f[3]); w.z = pk_bf16(f[4], f[5]); w.w = pk_bf16(f[6], f[7]); return w; }
; __device__ __forceinline__ int crow(int r, int hi) { return (r & 3) + 8 * (r >> 2) + 4 * hi; }
; template <bool SAMPLE> ...
;     ...
; #pragma unroll
;     for (int i = 0; i < 16; ++i) {
;         const int qq = crow(i, hi);
;         const float rl = wsf[qq];
; #pragma unroll
;         for (int d0 = 0; d0 < 2; ++d0) ost[qq * 64 + d0 * 32 + r32] = (bf16_t)(pk_bf16(o[d0][i] * rl, 0.f) & 0xffffu);
;     }
;     asm volatile("s_waitcnt lgkmcnt(0)" ::: "memory");
; #pragma unroll
;     for (int it4 = 0; it4 < 4; ++it4) {
;         const int qq = it4 * 8 + (lane >> 3), ch = lane & 7;
;         const int orow = SAMPLE ? row0 + (qq & 7) : row0 + qq;
;         const int ohead = SAMPLE ? head0 + (qq >> 3) : head0;
;         const u32x4 ow = *(const LAS u32x4*)(ost + qq * 64 + ch * 8);
;         float of[8], zf[8], yv[8];
;         unpack8(ow, of); unpack8(zw[it4], zf);
; #pragma unroll
;         for (int k = 0; k < 8; ++k) yv[k] = of[k] * zf[k];
;         *(u32x4*)(Y + (size_t)orow * D + 512 + ohead * 64 + ch * 8) = pack8(yv);
	v_mul_f32_e32 v0, v0, v32
	v_lshl_add_u32 v41, v98, 1, s1
	v_lshl_add_u32 v42, v97, 9, v41
	v_cvt_pk_bf16_f32 v0, v0, s0
	ds_write_b16 v42, v0
	v_mul_f32_e32 v0, v16, v32
	v_cvt_pk_bf16_f32 v0, v0, s0
	ds_write_b16 v42, v0 offset:64
	v_mul_f32_e32 v0, v1, v33
	v_cvt_pk_bf16_f32 v0, v0, s0
	v_lshl_add_u32 v16, v100, 7, v41
	ds_write_b16 v16, v0 offset:128
	v_mul_f32_e32 v0, v17, v33
	v_cvt_pk_bf16_f32 v0, v0, s0
	ds_write_b16 v16, v0 offset:192
	v_mul_f32_e32 v0, v2, v34
	v_cvt_pk_bf16_f32 v0, v0, s0
	ds_write_b16 v16, v0 offset:256
	v_mul_f32_e32 v0, v18, v34
	v_cvt_pk_bf16_f32 v0, v0, s0
	ds_write_b16 v16, v0 offset:320
	v_mul_f32_e32 v0, v3, v35
	v_cvt_pk_bf16_f32 v0, v0, s0
	ds_write_b16 v16, v0 offset:384
	v_mul_f32_e32 v0, v19, v35
	v_cvt_pk_bf16_f32 v0, v0, s0
	ds_write_b16 v16, v0 offset:448
	s_waitcnt lgkmcnt(8)
	v_mul_f32_e32 v0, v4, v36
	v_cvt_pk_bf16_f32 v0, v0, s0
	ds_write_b16 v16, v0 offset:1024
	v_mul_f32_e32 v0, v20, v36
	v_cvt_pk_bf16_f32 v0, v0, s0
	ds_write_b16 v16, v0 offset:1088
	v_mul_f32_e32 v0, v5, v37
	v_cvt_pk_bf16_f32 v0, v0, s0
	ds_write_b16 v16, v0 offset:1152
	v_mul_f32_e32 v0, v21, v37
	v_cvt_pk_bf16_f32 v0, v0, s0
	ds_write_b16 v16, v0 offset:1216
	v_mul_f32_e32 v0, v6, v38
	v_cvt_pk_bf16_f32 v0, v0, s0
	ds_write_b16 v16, v0 offset:1280
	v_mul_f32_e32 v0, v22, v38
	v_cvt_pk_bf16_f32 v0, v0, s0
	ds_write_b16 v16, v0 offset:1344
	v_mul_f32_e32 v0, v7, v39
	v_cvt_pk_bf16_f32 v0, v0, s0
	ds_write_b16 v16, v0 offset:1408
	ds_read_b128 v[0:3], v40 offset:64
	v_mul_f32_e32 v4, v23, v39
	v_cvt_pk_bf16_f32 v4, v4, s0
	ds_write_b16 v16, v4 offset:1472
	ds_read_b128 v[4:7], v40 offset:96
	s_waitcnt lgkmcnt(2)
	v_mul_f32_e32 v8, v8, v0
	v_mul_f32_e32 v0, v24, v0
	v_cvt_pk_bf16_f32 v0, v0, s0
	ds_write_b16 v16, v0 offset:2112
	v_mul_f32_e32 v0, v9, v1
	v_cvt_pk_bf16_f32 v0, v0, s0
	ds_write_b16 v16, v0 offset:2176
	v_mul_f32_e32 v0, v25, v1
	v_cvt_pk_bf16_f32 v0, v0, s0
	ds_write_b16 v16, v0 offset:2240
	v_mul_f32_e32 v0, v10, v2
	v_cvt_pk_bf16_f32 v0, v0, s0
	ds_write_b16 v16, v0 offset:2304
	v_mul_f32_e32 v0, v26, v2
	v_cvt_pk_bf16_f32 v0, v0, s0
	ds_write_b16 v16, v0 offset:2368
	v_mul_f32_e32 v0, v11, v3
	v_cvt_pk_bf16_f32 v0, v0, s0
	ds_write_b16 v16, v0 offset:2432
	v_mul_f32_e32 v0, v27, v3
	v_cvt_pk_bf16_f32 v0, v0, s0
	ds_write_b16 v16, v0 offset:2496
	s_waitcnt lgkmcnt(7)
	v_mul_f32_e32 v0, v12, v4
	v_cvt_pk_bf16_f32 v0, v0, s0
	ds_write_b16 v16, v0 offset:3072
	v_mul_f32_e32 v0, v28, v4
	v_cvt_pk_bf16_f32 v0, v0, s0
	ds_write_b16 v16, v0 offset:3136
	v_mul_f32_e32 v0, v13, v5
	v_cvt_pk_bf16_f32 v0, v0, s0
	ds_write_b16 v16, v0 offset:3200
	v_mul_f32_e32 v0, v29, v5
	v_cvt_pk_bf16_f32 v0, v0, s0
	ds_write_b16 v16, v0 offset:3264
	v_mul_f32_e32 v0, v14, v6
	v_cvt_pk_bf16_f32 v0, v0, s0
	ds_write_b16 v16, v0 offset:3328
	v_mul_f32_e32 v0, v30, v6
	v_cvt_pk_bf16_f32 v0, v0, s0
	ds_write_b16 v16, v0 offset:3392
	v_mul_f32_e32 v0, v15, v7
	v_cvt_pk_bf16_f32 v0, v0, s0
	ds_write_b16 v16, v0 offset:3456
	v_mul_f32_e32 v0, v31, v7
	v_cvt_pk_bf16_f32 v8, v8, s0
	v_cvt_pk_bf16_f32 v0, v0, s0
	ds_write_b16 v16, v8 offset:2048
	ds_write_b16 v16, v0 offset:3520
	v_or_b32_e32 v0, s0, v106
	v_lshlrev_b32_e32 v1, 7, v106
	s_waitcnt lgkmcnt(0)
	v_add3_u32 v18, s1, v1, v96
	v_ashrrev_i32_e32 v1, 31, v0
	v_lshlrev_b64 v[4:5], 11, v[0:1]
	ds_read_b128 v[0:3], v18
	v_lshl_add_u64 v[4:5], s[78:79], 0, v[4:5]
	v_mov_b32_e32 v97, v173
	v_lshl_add_u64 v[8:9], v[4:5], 0, v[96:97]
	ds_read_b128 v[4:7], v18 offset:1024
	s_waitcnt lgkmcnt(1)
; #define LAS __attribute__((address_space(3)))
; __device__ __forceinline__ u32x4 pack8(const float (&f)[8]) { u32x4 w; w.x = pk_bf16(f[0], f[1]); w.y = pk_bf16(f[2], f[3]); w.z = pk_bf16(f[4], f[5]); w.w = pk_bf16(f[6], f[7]); return w; }
; template <bool SAMPLE> ...
;     ...
; #pragma unroll
;     for (int it4 = 0; it4 < 4; ++it4) {
;         const int qq = it4 * 8 + (lane >> 3), ch = lane & 7;
;         const int orow = SAMPLE ? row0 + (qq & 7) : row0 + qq;
;         const int ohead = SAMPLE ? head0 + (qq >> 3) : head0;
;         const u32x4 ow = *(const LAS u32x4*)(ost + qq * 64 + ch * 8);
;         float of[8], zf[8], yv[8];
;         unpack8(ow, of); unpack8(zw[it4], zf);
; #pragma unroll
;         for (int k = 0; k < 8; ++k) yv[k] = of[k] * zf[k];
;         *(u32x4*)(Y + (size_t)orow * D + 512 + ohead * 64 + ch * 8) = pack8(yv);
;     }
	v_lshlrev_b32_e32 v10, 16, v0
	v_and_b32_e32 v11, 0xffff0000, v0
	v_lshlrev_b32_e32 v12, 16, v92
	v_and_b32_e32 v13, 0xffff0000, v92
	v_pk_mul_f32 v[10:11], v[12:13], v[10:11]
	v_lshlrev_b32_e32 v0, 16, v1
	v_and_b32_e32 v1, 0xffff0000, v1
	v_lshlrev_b32_e32 v12, 16, v93
	v_and_b32_e32 v13, 0xffff0000, v93
	v_readlane_b32 s0, v255, 26
	v_pk_mul_f32 v[12:13], v[12:13], v[0:1]
	v_lshlrev_b32_e32 v0, 16, v2
	v_and_b32_e32 v1, 0xffff0000, v2
	v_lshlrev_b32_e32 v14, 16, v94
	v_and_b32_e32 v15, 0xffff0000, v94
	v_readlane_b32 s1, v255, 27
	v_pk_mul_f32 v[14:15], v[14:15], v[0:1]
	v_lshlrev_b32_e32 v0, 16, v3
	v_and_b32_e32 v1, 0xffff0000, v3
	v_lshlrev_b32_e32 v2, 16, v95
	v_and_b32_e32 v3, 0xffff0000, v95
	v_lshl_add_u64 v[8:9], s[0:1], 1, v[8:9]
	s_mov_b64 s[0:1], 0x1800400
	v_pk_mul_f32 v[16:17], v[2:3], v[0:1]
	v_cvt_pk_bf16_f32 v0, v10, v11
	v_lshl_add_u64 v[10:11], v[8:9], 0, s[0:1]
	s_mov_b32 s0, 0x1800000
	v_add_co_u32_e32 v8, vcc, s0, v8
	v_cvt_pk_bf16_f32 v1, v12, v13
	v_cvt_pk_bf16_f32 v2, v14, v15
	v_cvt_pk_bf16_f32 v3, v16, v17
	v_addc_co_u32_e32 v9, vcc, 0, v9, vcc
	global_store_dwordx4 v[8:9], v[0:3], off offset:1024 sc1
	v_lshlrev_b32_e32 v8, 16, v90
	v_and_b32_e32 v9, 0xffff0000, v90
	s_waitcnt lgkmcnt(0)
	v_lshlrev_b32_e32 v0, 16, v4
	v_and_b32_e32 v1, 0xffff0000, v4
	v_lshlrev_b32_e32 v2, 16, v88
	v_and_b32_e32 v3, 0xffff0000, v88
	v_pk_mul_f32 v[0:1], v[2:3], v[0:1]
	v_lshlrev_b32_e32 v2, 16, v5
	v_and_b32_e32 v3, 0xffff0000, v5
	v_lshlrev_b32_e32 v4, 16, v89
	v_and_b32_e32 v5, 0xffff0000, v89
	v_pk_mul_f32 v[2:3], v[4:5], v[2:3]
	v_lshlrev_b32_e32 v4, 16, v6
	v_and_b32_e32 v5, 0xffff0000, v6
	v_pk_mul_f32 v[8:9], v[8:9], v[4:5]
	v_lshlrev_b32_e32 v4, 16, v7
	v_and_b32_e32 v5, 0xffff0000, v7
	v_lshlrev_b32_e32 v6, 16, v91
	v_and_b32_e32 v7, 0xffff0000, v91
	v_pk_mul_f32 v[12:13], v[6:7], v[4:5]
	ds_read_b128 v[4:7], v18 offset:2048
	v_cvt_pk_bf16_f32 v0, v0, v1
	v_cvt_pk_bf16_f32 v1, v2, v3
	v_cvt_pk_bf16_f32 v2, v8, v9
	v_cvt_pk_bf16_f32 v3, v12, v13
	global_store_dwordx4 v[10:11], v[0:3], off offset:128 sc1
	ds_read_b128 v[0:3], v18 offset:3072
	s_waitcnt lgkmcnt(1)
	v_lshlrev_b32_e32 v8, 16, v4
	v_and_b32_e32 v9, 0xffff0000, v4
	v_lshlrev_b32_e32 v12, 16, v84
	v_and_b32_e32 v13, 0xffff0000, v84
	v_pk_mul_f32 v[8:9], v[12:13], v[8:9]
	v_lshlrev_b32_e32 v4, 16, v5
	v_and_b32_e32 v5, 0xffff0000, v5
	v_lshlrev_b32_e32 v12, 16, v85
	v_and_b32_e32 v13, 0xffff0000, v85
	v_pk_mul_f32 v[12:13], v[12:13], v[4:5]
	v_lshlrev_b32_e32 v4, 16, v6
	v_and_b32_e32 v5, 0xffff0000, v6
	v_lshlrev_b32_e32 v14, 16, v86
	v_and_b32_e32 v15, 0xffff0000, v86
	v_pk_mul_f32 v[14:15], v[14:15], v[4:5]
	v_lshlrev_b32_e32 v4, 16, v7
	v_and_b32_e32 v5, 0xffff0000, v7
	v_lshlrev_b32_e32 v6, 16, v87
	v_and_b32_e32 v7, 0xffff0000, v87
	v_pk_mul_f32 v[16:17], v[6:7], v[4:5]
	v_cvt_pk_bf16_f32 v4, v8, v9
	v_cvt_pk_bf16_f32 v5, v12, v13
	v_cvt_pk_bf16_f32 v6, v14, v15
	v_cvt_pk_bf16_f32 v7, v16, v17
	global_store_dwordx4 v[10:11], v[4:7], off offset:256 sc1
	v_lshlrev_b32_e32 v8, 16, v82
	v_and_b32_e32 v9, 0xffff0000, v82
	s_waitcnt lgkmcnt(0)
	v_lshlrev_b32_e32 v4, 16, v0
	v_and_b32_e32 v5, 0xffff0000, v0
	v_lshlrev_b32_e32 v6, 16, v80
	v_and_b32_e32 v7, 0xffff0000, v80
	v_pk_mul_f32 v[4:5], v[6:7], v[4:5]
	v_lshlrev_b32_e32 v0, 16, v1
	v_and_b32_e32 v1, 0xffff0000, v1
	v_lshlrev_b32_e32 v6, 16, v81
	v_and_b32_e32 v7, 0xffff0000, v81
	v_pk_mul_f32 v[6:7], v[6:7], v[0:1]
	v_lshlrev_b32_e32 v0, 16, v2
	v_and_b32_e32 v1, 0xffff0000, v2
	v_pk_mul_f32 v[8:9], v[8:9], v[0:1]
	v_lshlrev_b32_e32 v0, 16, v3
	v_and_b32_e32 v1, 0xffff0000, v3
	v_lshlrev_b32_e32 v2, 16, v83
	v_and_b32_e32 v3, 0xffff0000, v83
	v_pk_mul_f32 v[12:13], v[2:3], v[0:1]
	v_cvt_pk_bf16_f32 v0, v4, v5
	v_cvt_pk_bf16_f32 v1, v6, v7
	v_cvt_pk_bf16_f32 v2, v8, v9
	v_cvt_pk_bf16_f32 v3, v12, v13
	global_store_dwordx4 v[10:11], v[0:3], off offset:384 sc1
	s_waitcnt lgkmcnt(0)

; __device__ __forceinline__ unsigned xb_add(unsigned* p, unsigned v) { return __hip_atomic_fetch_add(p, v, __ATOMIC_RELAXED, __HIP_MEMORY_SCOPE_AGENT); }
; __device__ __forceinline__ void xcd_barrier(const XcdBarrier& b) {
;     asm volatile("s_waitcnt vmcnt(0)" ::: "memory");
;     __syncthreads();
;     if (threadIdx.x == 0) {
;         unsigned* bar = b.bar;
;         __builtin_amdgcn_s_waitcnt(0);
;         unsigned nloc = b.st[0], nx = b.st[1];
;         if (nloc == 0u) { xcd_barrier_complete(bar, b.x, nloc, nx); b.st[0] = nloc; b.st[1] = nx; }
;         const unsigned old = xb_add(&bar[XB_XSUB(b.x)], 1u);
;         const unsigned gen = old / nloc;
;         if (old + 1u == (gen + 1u) * nloc) {
;             __builtin_amdgcn_fence(__ATOMIC_RELEASE, "agent");
;             asm volatile("s_waitcnt vmcnt(0)" ::: "memory");
;             const unsigned og = xb_add(&bar[XB_TOP], 1u);
;             const unsigned tg = og / nx;
;             if (og + 1u == (tg + 1u) * nx) xb_add(&bar[XB_TOPGEN], 1u);
.LBB0_534:
	s_and_b64 vcc, exec, s[0:1]
	s_mov_b32 s93, s4
	s_cbranch_vccz .LBB0_441
	s_getreg_b32 s2, hwreg(HW_REG_XCC_ID, 0, 4)
	s_waitcnt vmcnt(0)
	s_barrier
	s_mov_b64 s[0:1], exec
	v_readlane_b32 s4, v253, 2
	v_readlane_b32 s5, v253, 3
	v_readlane_b32 s72, v254, 48
	v_readlane_b32 s80, v254, 50
	v_readlane_b32 s82, v254, 52
	v_readlane_b32 s92, v254, 54
	v_readlane_b32 s94, v254, 56
	v_readlane_b32 s98, v254, 58
	v_readlane_b32 s54, v254, 60
	v_readlane_b32 s56, v254, 62
	v_readlane_b32 s60, v255, 0
	v_readlane_b32 s62, v255, 2
	v_readlane_b32 s22, v255, 21
	s_and_b64 s[4:5], s[0:1], s[4:5]
	v_readlane_b32 s73, v254, 49
	v_readlane_b32 s81, v254, 51
	v_readlane_b32 s83, v254, 53
	v_readlane_b32 s93, v254, 55
	v_readlane_b32 s95, v254, 57
	v_readlane_b32 s99, v254, 59
	v_readlane_b32 s55, v254, 61
	v_readlane_b32 s57, v254, 63
	v_readlane_b32 s61, v255, 1
	v_readlane_b32 s63, v255, 3
	v_readlane_b32 s33, v255, 4
	v_readlane_b32 s85, v255, 5
	v_readlane_b32 s25, v254, 41
	v_readlane_b32 s28, v254, 43
	v_readlane_b32 s23, v255, 22
	s_mov_b64 exec, s[4:5]
	s_cbranch_execz .LBB0_587
	v_mov_b32_e32 v0, 0x20020
	s_waitcnt vmcnt(0) lgkmcnt(0)
	ds_read2_b32 v[2:3], v0 offset1:1
	s_and_b32 s3, s2, 15
	s_lshl_b32 s3, s3, 8
	s_add_u32 s6, s78, 0x1701400
	s_addc_u32 s7, s79, 0
	s_add_u32 s6, s6, s3
	s_addc_u32 s7, s7, 0
	s_add_u32 s8, s6, 0x1000
	s_addc_u32 s9, s7, 0
	s_add_u32 s10, s78, 0x1703400
	s_addc_u32 s11, s79, 0
	s_waitcnt lgkmcnt(0)
	v_readfirstlane_b32 s30, v2
	v_readfirstlane_b32 s31, v3
	s_nop 3
	s_cmp_eq_u32 s30, 0
	s_cbranch_scc1 .Lxb_slow_m
	v_readlane_b32 s29, v255, 21
	s_nop 3
	s_lshl_b32 s29, s29, 2
	s_add_i32 s29, s29, 3
	global_atomic_add v2, v173, v212, s[6:7] sc0
	buffer_inv sc1
	s_add_i32 s32, s29, 1
	s_mul_i32 s5, s32, s30
	s_mul_i32 s32, s32, s31
	s_waitcnt vmcnt(1)
	v_readfirstlane_b32 s3, v2
	s_nop 3
	s_add_i32 s3, s3, 1
	s_cmp_lg_u32 s3, s5
	s_cbranch_scc1 .Lxb_local_m
	global_atomic_add v173, v212, s[10:11]
	s_mov_b32 s3, 0
